# EpiResid epilogues (out-proj, FFN-down, final): residual loads issued up front into free VGPR quads with counted vmcnt instead of load-wait-store ladder; FFN-up epilogue 32-bit store offsets + resched
# speedup vs baseline: 1.0049x; 1.0049x over previous
.LBB0_647:
	v_lshl_add_u32 v142, s52, 8, v144
	v_ashrrev_i32_e32 v143, 31, v142
	v_lshl_or_b32 v140, s28, 8, v146
	v_lshlrev_b64 v[138:139], 11, v[142:143]
	v_ashrrev_i32_e32 v141, 31, v140
	v_lshl_add_u64 v[138:139], s[14:15], 0, v[138:139]
	v_lshl_add_u64 v[138:139], v[140:141], 1, v[138:139]
	v_subrev_u32_e32 v240, s14, v138
	global_load_dwordx4 v[184:187], v240, s[14:15]
	global_load_dwordx4 v[188:191], v240, s[14:15] offset:256
	v_add_u32_e32 v241, 0x8000, v240
	global_load_dwordx4 v[192:195], v241, s[14:15]
	v_add_u32_e32 v241, 0x8000, v240
	global_load_dwordx4 v[196:199], v241, s[14:15] offset:256
	v_add_u32_e32 v241, 0x10000, v240
	global_load_dwordx4 v[200:203], v241, s[14:15]
	v_add_u32_e32 v241, 0x10000, v240
	global_load_dwordx4 v[204:207], v241, s[14:15] offset:256
	v_add_u32_e32 v241, 0x18000, v240
	global_load_dwordx4 v[208:211], v241, s[14:15]
	v_add_u32_e32 v241, 0x18000, v240
	global_load_dwordx4 v[212:215], v241, s[14:15] offset:256
	v_add_u32_e32 v241, 0x40000, v240
	global_load_dwordx4 v[220:223], v241, s[14:15]
	v_add_u32_e32 v241, 0x40000, v240
	global_load_dwordx4 v[224:227], v241, s[14:15] offset:256
	v_add_u32_e32 v241, 0x48000, v240
	global_load_dwordx4 v[228:231], v241, s[14:15]
	v_add_u32_e32 v241, 0x48000, v240
	global_load_dwordx4 v[232:235], v241, s[14:15] offset:256
	s_waitcnt vmcnt(11)
	s_nop 1
	v_mov_b64_e32 v[150:151], v[184:185]
	v_mov_b64_e32 v[152:153], v[186:187]
	v_add_u32_e32 v241, 0x50000, v240
	global_load_dwordx4 v[184:187], v241, s[14:15]
	s_waitcnt vmcnt(11)
	s_nop 1
	v_mov_b64_e32 v[154:155], v[188:189]
	v_mov_b64_e32 v[156:157], v[190:191]
	v_add_u32_e32 v241, 0x50000, v240
	global_load_dwordx4 v[188:191], v241, s[14:15] offset:256
	v_and_b32_e32 v149, 64, v217
	v_xor_b32_e32 v148, 16, v217
	v_add_u32_e32 v149, 64, v149
	v_xor_b32_e32 v158, 32, v217
	v_cmp_lt_i32_e32 vcc, v148, v149
	v_and_b32_e32 v159, 0xffff0000, v150
	v_cndmask_b32_e32 v148, v217, v148, vcc
	v_cmp_lt_i32_e32 vcc, v158, v149
	v_lshlrev_b32_e32 v149, 2, v148
	v_lshlrev_b32_e32 v176, 16, v154
	v_cndmask_b32_e32 v158, v217, v158, vcc
	v_lshlrev_b32_e32 v148, 2, v158
	v_lshlrev_b32_e32 v158, 16, v150
	v_lshlrev_b32_e32 v150, 16, v151
	v_and_b32_e32 v151, 0xffff0000, v151
	v_and_b32_e32 v177, 0xffff0000, v154
	v_lshlrev_b32_e32 v154, 16, v155
	v_and_b32_e32 v155, 0xffff0000, v155
	v_pk_add_f32 v[124:125], v[124:125], v[158:159]
	v_lshlrev_b32_e32 v174, 16, v152
	v_and_b32_e32 v175, 0xffff0000, v152
	v_lshlrev_b32_e32 v152, 16, v153
	v_and_b32_e32 v153, 0xffff0000, v153
	v_lshlrev_b32_e32 v178, 16, v156
	v_and_b32_e32 v179, 0xffff0000, v156
	v_lshlrev_b32_e32 v156, 16, v157
	v_and_b32_e32 v157, 0xffff0000, v157
	v_pk_add_f32 v[126:127], v[126:127], v[150:151]
	v_pk_add_f32 v[118:119], v[118:119], v[154:155]
	v_pk_mul_f32 v[154:155], v[124:125], v[124:125]
	v_pk_add_f32 v[122:123], v[122:123], v[152:153]
	v_pk_add_f32 v[152:153], v[114:115], v[156:157]
	v_pk_mul_f32 v[156:157], v[126:127], v[126:127]
	v_add_f32_e32 v115, v154, v155
	v_pk_add_f32 v[120:121], v[120:121], v[174:175]
	v_add_f32_e32 v115, v156, v115
	v_pk_mul_f32 v[158:159], v[120:121], v[120:121]
	v_add_f32_e32 v115, v157, v115
	v_add_f32_e32 v115, v158, v115
	v_pk_mul_f32 v[174:175], v[122:123], v[122:123]
	v_add_f32_e32 v115, v159, v115
	v_pk_add_f32 v[116:117], v[116:117], v[176:177]
	v_add_f32_e32 v115, v174, v115
	v_cvt_pk_bf16_f32 v114, v120, v121
	v_pk_mul_f32 v[120:121], v[116:117], v[116:117]
	v_add_f32_e32 v115, v175, v115
	v_add_f32_e32 v115, v120, v115
	v_pk_add_f32 v[150:151], v[112:113], v[178:179]
	v_cvt_pk_bf16_f32 v112, v124, v125
	v_pk_mul_f32 v[124:125], v[118:119], v[118:119]
	v_add_f32_e32 v115, v121, v115
	v_add_f32_e32 v115, v124, v115
	v_cvt_pk_bf16_f32 v113, v126, v127
	v_pk_mul_f32 v[126:127], v[150:151], v[150:151]
	v_add_f32_e32 v115, v125, v115
	v_add_f32_e32 v115, v126, v115
	v_pk_mul_f32 v[176:177], v[152:153], v[152:153]
	v_add_f32_e32 v115, v127, v115
	v_add_f32_e32 v115, v176, v115
	v_add_f32_e32 v120, v177, v115
	ds_bpermute_b32 v121, v149, v120
	v_cvt_pk_bf16_f32 v115, v122, v123
	global_store_dwordx4 v[138:139], v[112:115], off
	v_cvt_pk_bf16_f32 v116, v116, v117
	v_cvt_pk_bf16_f32 v117, v118, v119
	s_waitcnt lgkmcnt(0)
	v_add_f32_e32 v114, v120, v121
	ds_bpermute_b32 v115, v148, v114
	v_cvt_pk_bf16_f32 v118, v150, v151
	v_cvt_pk_bf16_f32 v119, v152, v153
	v_lshl_add_u64 v[112:113], v[142:143], 2, s[10:11]
	global_store_dwordx4 v[138:139], v[116:119], off offset:256
	s_and_saveexec_b64 s[28:29], s[4:5]
	s_cbranch_execz .LBB0_649
	s_waitcnt lgkmcnt(0)
	v_add_f32_e32 v114, v114, v115
	global_atomic_add_f32 v[112:113], v114, off
.LBB0_649:
	s_or_b64 exec, exec, s[28:29]
	v_or_b32_e32 v114, 16, v142
	s_waitcnt lgkmcnt(0)
	v_ashrrev_i32_e32 v115, 31, v114
	v_lshlrev_b64 v[114:115], 11, v[114:115]
	v_lshl_add_u64 v[114:115], s[14:15], 0, v[114:115]
	v_lshl_add_u64 v[114:115], v[140:141], 1, v[114:115]
	s_waitcnt vmcnt(11)
	s_nop 1
	v_mov_b64_e32 v[116:117], v[192:193]
	v_mov_b64_e32 v[118:119], v[194:195]
	v_add_u32_e32 v241, 0x58000, v240
	global_load_dwordx4 v[192:195], v241, s[14:15]
	s_waitcnt vmcnt(11)
	s_nop 1
	v_mov_b64_e32 v[120:121], v[196:197]
	v_mov_b64_e32 v[122:123], v[198:199]
	v_add_u32_e32 v241, 0x58000, v240
	global_load_dwordx4 v[196:199], v241, s[14:15] offset:256
	v_lshlrev_b32_e32 v124, 16, v116
	v_and_b32_e32 v125, 0xffff0000, v116
	v_lshlrev_b32_e32 v116, 16, v117
	v_and_b32_e32 v117, 0xffff0000, v117
	v_lshlrev_b32_e32 v126, 16, v118
	v_and_b32_e32 v127, 0xffff0000, v118
	v_lshlrev_b32_e32 v118, 16, v119
	v_and_b32_e32 v119, 0xffff0000, v119
	v_lshlrev_b32_e32 v152, 16, v122
	v_and_b32_e32 v153, 0xffff0000, v122
	v_lshlrev_b32_e32 v122, 16, v123
	v_and_b32_e32 v123, 0xffff0000, v123
	v_pk_add_f32 v[108:109], v[108:109], v[124:125]
	v_lshlrev_b32_e32 v150, 16, v120
	v_and_b32_e32 v151, 0xffff0000, v120
	v_lshlrev_b32_e32 v120, 16, v121
	v_and_b32_e32 v121, 0xffff0000, v121
	v_pk_add_f32 v[110:111], v[110:111], v[116:117]
	v_pk_add_f32 v[106:107], v[106:107], v[118:119]
	v_pk_add_f32 v[118:119], v[98:99], v[122:123]
	v_pk_mul_f32 v[98:99], v[108:109], v[108:109]
	v_pk_add_f32 v[102:103], v[102:103], v[120:121]
	v_pk_mul_f32 v[120:121], v[110:111], v[110:111]
	v_add_f32_e32 v98, v98, v99
	v_pk_add_f32 v[104:105], v[104:105], v[126:127]
	v_add_f32_e32 v98, v120, v98
	v_pk_mul_f32 v[122:123], v[104:105], v[104:105]
	v_add_f32_e32 v98, v121, v98
	v_add_f32_e32 v98, v122, v98
	v_pk_mul_f32 v[124:125], v[106:107], v[106:107]
	v_add_f32_e32 v98, v123, v98
	v_pk_add_f32 v[100:101], v[100:101], v[150:151]
	v_add_f32_e32 v98, v124, v98
	v_pk_add_f32 v[116:117], v[96:97], v[152:153]
	v_cvt_pk_bf16_f32 v96, v108, v109
	v_pk_mul_f32 v[108:109], v[100:101], v[100:101]
	v_add_f32_e32 v98, v125, v98
	v_add_f32_e32 v98, v108, v98
	v_cvt_pk_bf16_f32 v97, v110, v111
	v_pk_mul_f32 v[110:111], v[102:103], v[102:103]
	v_add_f32_e32 v98, v109, v98
	v_add_f32_e32 v98, v110, v98
	v_pk_mul_f32 v[126:127], v[116:117], v[116:117]
	v_add_f32_e32 v98, v111, v98
	v_add_f32_e32 v98, v126, v98
	v_pk_mul_f32 v[150:151], v[118:119], v[118:119]
	v_add_f32_e32 v98, v127, v98
	v_add_f32_e32 v98, v150, v98
	v_add_f32_e32 v108, v151, v98
	ds_bpermute_b32 v109, v149, v108
	v_cvt_pk_bf16_f32 v98, v104, v105
	v_cvt_pk_bf16_f32 v99, v106, v107
	global_store_dwordx4 v[114:115], v[96:99], off
	s_waitcnt lgkmcnt(0)
	s_nop 0
	v_add_f32_e32 v96, v108, v109
	ds_bpermute_b32 v97, v148, v96
	v_cvt_pk_bf16_f32 v98, v100, v101
	v_cvt_pk_bf16_f32 v99, v102, v103
	v_cvt_pk_bf16_f32 v100, v116, v117
	v_cvt_pk_bf16_f32 v101, v118, v119
	global_store_dwordx4 v[114:115], v[98:101], off offset:256
	s_and_saveexec_b64 s[28:29], s[4:5]
	s_cbranch_execz .LBB0_651
	s_waitcnt lgkmcnt(0)
	v_add_f32_e32 v96, v96, v97
	global_atomic_add_f32 v[112:113], v96, off offset:64
.LBB0_651:
	s_or_b64 exec, exec, s[28:29]
	v_or_b32_e32 v96, 32, v142
	s_waitcnt lgkmcnt(0)
	v_ashrrev_i32_e32 v97, 31, v96
	v_lshlrev_b64 v[96:97], 11, v[96:97]
	v_lshl_add_u64 v[96:97], s[14:15], 0, v[96:97]
	v_lshl_add_u64 v[96:97], v[140:141], 1, v[96:97]
	s_waitcnt vmcnt(11)
	s_nop 1
	v_mov_b64_e32 v[98:99], v[200:201]
	v_mov_b64_e32 v[100:101], v[202:203]
	s_waitcnt vmcnt(10)
	s_nop 1
	v_mov_b64_e32 v[102:103], v[204:205]
	v_mov_b64_e32 v[104:105], v[206:207]
	v_lshlrev_b32_e32 v106, 16, v98
	v_and_b32_e32 v107, 0xffff0000, v98
	v_lshlrev_b32_e32 v98, 16, v99
	v_and_b32_e32 v99, 0xffff0000, v99
	v_lshlrev_b32_e32 v108, 16, v100
	v_and_b32_e32 v109, 0xffff0000, v100
	v_lshlrev_b32_e32 v100, 16, v101
	v_and_b32_e32 v101, 0xffff0000, v101
	v_lshlrev_b32_e32 v114, 16, v104
	v_and_b32_e32 v115, 0xffff0000, v104
	v_lshlrev_b32_e32 v104, 16, v105
	v_and_b32_e32 v105, 0xffff0000, v105
	v_pk_add_f32 v[92:93], v[92:93], v[106:107]
	v_lshlrev_b32_e32 v110, 16, v102
	v_and_b32_e32 v111, 0xffff0000, v102
	v_lshlrev_b32_e32 v102, 16, v103
	v_and_b32_e32 v103, 0xffff0000, v103
	v_pk_add_f32 v[94:95], v[94:95], v[98:99]
	v_pk_add_f32 v[90:91], v[90:91], v[100:101]
	v_pk_add_f32 v[100:101], v[82:83], v[104:105]
	v_pk_mul_f32 v[82:83], v[92:93], v[92:93]
	v_pk_add_f32 v[86:87], v[86:87], v[102:103]
	v_pk_mul_f32 v[102:103], v[94:95], v[94:95]
	v_add_f32_e32 v82, v82, v83
	v_pk_add_f32 v[88:89], v[88:89], v[108:109]
	v_add_f32_e32 v82, v102, v82
	v_pk_mul_f32 v[104:105], v[88:89], v[88:89]
	v_add_f32_e32 v82, v103, v82
	v_add_f32_e32 v82, v104, v82
	v_pk_mul_f32 v[106:107], v[90:91], v[90:91]
	v_add_f32_e32 v82, v105, v82
	v_pk_add_f32 v[84:85], v[84:85], v[110:111]
	v_add_f32_e32 v82, v106, v82
	v_pk_add_f32 v[98:99], v[80:81], v[114:115]
	v_cvt_pk_bf16_f32 v80, v92, v93
	v_pk_mul_f32 v[92:93], v[84:85], v[84:85]
	v_add_f32_e32 v82, v107, v82
	v_add_f32_e32 v82, v92, v82
	v_cvt_pk_bf16_f32 v81, v94, v95
	v_pk_mul_f32 v[94:95], v[86:87], v[86:87]
	v_add_f32_e32 v82, v93, v82
	v_add_f32_e32 v82, v94, v82
	v_pk_mul_f32 v[108:109], v[98:99], v[98:99]
	v_add_f32_e32 v82, v95, v82
	v_add_f32_e32 v82, v108, v82
	v_pk_mul_f32 v[110:111], v[100:101], v[100:101]
	v_add_f32_e32 v82, v109, v82
	v_add_f32_e32 v82, v110, v82
	v_add_f32_e32 v92, v111, v82
	ds_bpermute_b32 v93, v149, v92
	v_cvt_pk_bf16_f32 v82, v88, v89
	v_cvt_pk_bf16_f32 v83, v90, v91
	global_store_dwordx4 v[96:97], v[80:83], off
	s_waitcnt lgkmcnt(0)
	s_nop 0
	v_add_f32_e32 v80, v92, v93
	ds_bpermute_b32 v81, v148, v80
	v_cvt_pk_bf16_f32 v82, v84, v85
	v_cvt_pk_bf16_f32 v83, v86, v87
	v_cvt_pk_bf16_f32 v84, v98, v99
	v_cvt_pk_bf16_f32 v85, v100, v101
	global_store_dwordx4 v[96:97], v[82:85], off offset:256
	s_and_saveexec_b64 s[28:29], s[4:5]
	s_cbranch_execz .LBB0_653
	s_waitcnt lgkmcnt(0)
	v_add_f32_e32 v80, v80, v81
	global_atomic_add_f32 v[112:113], v80, off offset:128
.LBB0_653:
	s_or_b64 exec, exec, s[28:29]
	v_or_b32_e32 v80, 48, v142
	s_waitcnt lgkmcnt(0)
	v_ashrrev_i32_e32 v81, 31, v80
	v_lshlrev_b64 v[80:81], 11, v[80:81]
	v_lshl_add_u64 v[80:81], s[14:15], 0, v[80:81]
	v_lshl_add_u64 v[80:81], v[140:141], 1, v[80:81]
	s_waitcnt vmcnt(9)
	s_nop 1
	v_mov_b64_e32 v[82:83], v[208:209]
	v_mov_b64_e32 v[84:85], v[210:211]
	s_waitcnt vmcnt(8)
	s_nop 1
	v_mov_b64_e32 v[86:87], v[212:213]
	v_mov_b64_e32 v[88:89], v[214:215]
	v_lshlrev_b32_e32 v90, 16, v82
	v_and_b32_e32 v91, 0xffff0000, v82
	v_lshlrev_b32_e32 v82, 16, v83
	v_and_b32_e32 v83, 0xffff0000, v83
	v_lshlrev_b32_e32 v92, 16, v84
	v_and_b32_e32 v93, 0xffff0000, v84
	v_lshlrev_b32_e32 v84, 16, v85
	v_and_b32_e32 v85, 0xffff0000, v85
	v_lshlrev_b32_e32 v96, 16, v88
	v_and_b32_e32 v97, 0xffff0000, v88
	v_lshlrev_b32_e32 v88, 16, v89
	v_and_b32_e32 v89, 0xffff0000, v89
	v_pk_add_f32 v[76:77], v[76:77], v[90:91]
	v_lshlrev_b32_e32 v94, 16, v86
	v_and_b32_e32 v95, 0xffff0000, v86
	v_lshlrev_b32_e32 v86, 16, v87
	v_and_b32_e32 v87, 0xffff0000, v87
	v_pk_add_f32 v[78:79], v[78:79], v[82:83]
	v_pk_add_f32 v[74:75], v[74:75], v[84:85]
	v_pk_add_f32 v[84:85], v[66:67], v[88:89]
	v_pk_mul_f32 v[66:67], v[76:77], v[76:77]
	v_pk_add_f32 v[70:71], v[70:71], v[86:87]
	v_pk_mul_f32 v[86:87], v[78:79], v[78:79]
	v_add_f32_e32 v66, v66, v67
	v_pk_add_f32 v[72:73], v[72:73], v[92:93]
	v_add_f32_e32 v66, v86, v66
	v_pk_mul_f32 v[88:89], v[72:73], v[72:73]
	v_add_f32_e32 v66, v87, v66
	v_add_f32_e32 v66, v88, v66
	v_pk_mul_f32 v[90:91], v[74:75], v[74:75]
	v_add_f32_e32 v66, v89, v66
	v_pk_add_f32 v[68:69], v[68:69], v[94:95]
	v_add_f32_e32 v66, v90, v66
	v_pk_add_f32 v[82:83], v[64:65], v[96:97]
	v_cvt_pk_bf16_f32 v64, v76, v77
	v_pk_mul_f32 v[76:77], v[68:69], v[68:69]
	v_add_f32_e32 v66, v91, v66
	v_add_f32_e32 v66, v76, v66
	v_cvt_pk_bf16_f32 v65, v78, v79
	v_pk_mul_f32 v[78:79], v[70:71], v[70:71]
	v_add_f32_e32 v66, v77, v66
	v_add_f32_e32 v66, v78, v66
	v_pk_mul_f32 v[92:93], v[82:83], v[82:83]
	v_add_f32_e32 v66, v79, v66
	v_add_f32_e32 v66, v92, v66
	v_pk_mul_f32 v[94:95], v[84:85], v[84:85]
	v_add_f32_e32 v66, v93, v66
	v_add_f32_e32 v66, v94, v66
	v_add_f32_e32 v76, v95, v66
	ds_bpermute_b32 v77, v149, v76
	v_cvt_pk_bf16_f32 v66, v72, v73
	v_cvt_pk_bf16_f32 v67, v74, v75
	global_store_dwordx4 v[80:81], v[64:67], off
	s_waitcnt lgkmcnt(0)
	s_nop 0
	v_add_f32_e32 v64, v76, v77
	ds_bpermute_b32 v65, v148, v64
	v_cvt_pk_bf16_f32 v66, v68, v69
	v_cvt_pk_bf16_f32 v67, v70, v71
	v_cvt_pk_bf16_f32 v68, v82, v83
	v_cvt_pk_bf16_f32 v69, v84, v85
	global_store_dwordx4 v[80:81], v[66:69], off offset:256
	s_and_saveexec_b64 s[28:29], s[4:5]
	s_cbranch_execz .LBB0_655
	s_waitcnt lgkmcnt(0)
	v_add_f32_e32 v64, v64, v65
	global_atomic_add_f32 v[112:113], v64, off offset:192
.LBB0_655:
	s_or_b64 exec, exec, s[28:29]
	v_add_co_u32_e32 v70, vcc, 0x40000, v138
	s_mov_b64 s[28:29], 0x40000
	s_nop 0
	v_addc_co_u32_e32 v71, vcc, 0, v139, vcc
	s_waitcnt vmcnt(7)
	s_nop 1
	v_mov_b64_e32 v[66:67], v[220:221]
	v_mov_b64_e32 v[68:69], v[222:223]
	s_waitcnt lgkmcnt(0)
	v_lshl_add_u64 v[64:65], v[138:139], 0, s[28:29]
	v_lshlrev_b32_e32 v72, 16, v66
	v_and_b32_e32 v73, 0xffff0000, v66
	v_lshlrev_b32_e32 v66, 16, v67
	v_and_b32_e32 v67, 0xffff0000, v67
	v_pk_add_f32 v[62:63], v[62:63], v[66:67]
	v_lshlrev_b32_e32 v66, 16, v68
	v_and_b32_e32 v67, 0xffff0000, v68
	v_pk_add_f32 v[66:67], v[56:57], v[66:67]
	v_lshlrev_b32_e32 v56, 16, v69
	v_and_b32_e32 v57, 0xffff0000, v69
	v_pk_add_f32 v[60:61], v[60:61], v[72:73]
	v_pk_add_f32 v[68:69], v[58:59], v[56:57]
	v_cvt_pk_bf16_f32 v56, v60, v61
	v_cvt_pk_bf16_f32 v57, v62, v63
	v_cvt_pk_bf16_f32 v58, v66, v67
	v_cvt_pk_bf16_f32 v59, v68, v69
	global_store_dwordx4 v[70:71], v[56:59], off
	s_waitcnt vmcnt(6)
	s_nop 1
	v_mov_b64_e32 v[56:57], v[224:225]
	v_mov_b64_e32 v[58:59], v[226:227]
	v_pk_mul_f32 v[72:73], v[60:61], v[60:61]
	v_pk_mul_f32 v[74:75], v[62:63], v[62:63]
	v_pk_mul_f32 v[76:77], v[66:67], v[66:67]
	v_add_f32_e32 v66, v72, v73
	v_add_f32_e32 v66, v74, v66
	v_add_f32_e32 v66, v75, v66
	v_add_f32_e32 v66, v76, v66
	v_pk_mul_f32 v[78:79], v[68:69], v[68:69]
	v_add_f32_e32 v66, v77, v66
	v_add_f32_e32 v66, v78, v66
	v_add_f32_e32 v66, v79, v66
	v_lshlrev_b32_e32 v60, 16, v56
	v_and_b32_e32 v61, 0xffff0000, v56
	v_lshlrev_b32_e32 v56, 16, v57
	v_and_b32_e32 v57, 0xffff0000, v57
	v_pk_add_f32 v[54:55], v[54:55], v[56:57]
	v_lshlrev_b32_e32 v56, 16, v58
	v_and_b32_e32 v57, 0xffff0000, v58
	v_pk_add_f32 v[52:53], v[52:53], v[60:61]
	v_pk_add_f32 v[56:57], v[48:49], v[56:57]
	v_lshlrev_b32_e32 v48, 16, v59
	v_and_b32_e32 v49, 0xffff0000, v59
	v_pk_add_f32 v[58:59], v[50:51], v[48:49]
	v_pk_mul_f32 v[48:49], v[52:53], v[52:53]
	v_pk_mul_f32 v[50:51], v[54:55], v[54:55]
	v_add_f32_e32 v48, v48, v66
	v_add_f32_e32 v48, v49, v48
	v_add_f32_e32 v48, v50, v48
	v_pk_mul_f32 v[60:61], v[56:57], v[56:57]
	v_add_f32_e32 v48, v51, v48
	v_add_f32_e32 v48, v60, v48
	v_pk_mul_f32 v[62:63], v[58:59], v[58:59]
	v_add_f32_e32 v48, v61, v48
	v_add_f32_e32 v48, v62, v48
	v_add_f32_e32 v60, v63, v48
	v_cvt_pk_bf16_f32 v48, v52, v53
	v_cvt_pk_bf16_f32 v49, v54, v55
	v_cvt_pk_bf16_f32 v50, v56, v57
	v_cvt_pk_bf16_f32 v51, v58, v59
	global_store_dwordx4 v[64:65], v[48:51], off offset:256
	ds_bpermute_b32 v48, v149, v60
	s_waitcnt lgkmcnt(0)
	v_add_f32_e32 v48, v60, v48
	ds_bpermute_b32 v49, v148, v48
	s_and_saveexec_b64 s[28:29], s[4:5]
	s_cbranch_execz .LBB0_657
	s_waitcnt lgkmcnt(0)
	v_add_f32_e32 v48, v48, v49
	global_atomic_add_f32 v[112:113], v48, off offset:512
.LBB0_657:
	s_or_b64 exec, exec, s[28:29]
	v_add_co_u32_e32 v54, vcc, 0x48000, v138
	s_mov_b64 s[28:29], 0x48000
	s_nop 0
	v_addc_co_u32_e32 v55, vcc, 0, v139, vcc
	s_waitcnt vmcnt(5)
	s_nop 1
	v_mov_b64_e32 v[50:51], v[228:229]
	v_mov_b64_e32 v[52:53], v[230:231]
	s_waitcnt lgkmcnt(0)
	v_lshl_add_u64 v[48:49], v[138:139], 0, s[28:29]
	v_lshlrev_b32_e32 v56, 16, v50
	v_and_b32_e32 v57, 0xffff0000, v50
	v_lshlrev_b32_e32 v50, 16, v51
	v_and_b32_e32 v51, 0xffff0000, v51
	v_pk_add_f32 v[46:47], v[46:47], v[50:51]
	v_lshlrev_b32_e32 v50, 16, v52
	v_and_b32_e32 v51, 0xffff0000, v52
	v_pk_add_f32 v[50:51], v[40:41], v[50:51]
	v_lshlrev_b32_e32 v40, 16, v53
	v_and_b32_e32 v41, 0xffff0000, v53
	v_pk_add_f32 v[44:45], v[44:45], v[56:57]
	v_pk_add_f32 v[52:53], v[42:43], v[40:41]
	v_cvt_pk_bf16_f32 v40, v44, v45
	v_cvt_pk_bf16_f32 v41, v46, v47
	v_cvt_pk_bf16_f32 v42, v50, v51
	v_cvt_pk_bf16_f32 v43, v52, v53
	global_store_dwordx4 v[54:55], v[40:43], off
	s_waitcnt vmcnt(4)
	s_nop 1
	v_mov_b64_e32 v[40:41], v[232:233]
	v_mov_b64_e32 v[42:43], v[234:235]
	v_pk_mul_f32 v[56:57], v[44:45], v[44:45]
	v_pk_mul_f32 v[58:59], v[46:47], v[46:47]
	v_pk_mul_f32 v[60:61], v[50:51], v[50:51]
	v_add_f32_e32 v50, v56, v57
	v_add_f32_e32 v50, v58, v50
	v_add_f32_e32 v50, v59, v50
	v_add_f32_e32 v50, v60, v50
	v_pk_mul_f32 v[62:63], v[52:53], v[52:53]
	v_add_f32_e32 v50, v61, v50
	v_add_f32_e32 v50, v62, v50
	v_add_f32_e32 v50, v63, v50
	v_lshlrev_b32_e32 v44, 16, v40
	v_and_b32_e32 v45, 0xffff0000, v40
	v_lshlrev_b32_e32 v40, 16, v41
	v_and_b32_e32 v41, 0xffff0000, v41
	v_pk_add_f32 v[38:39], v[38:39], v[40:41]
	v_lshlrev_b32_e32 v40, 16, v42
	v_and_b32_e32 v41, 0xffff0000, v42
	v_pk_add_f32 v[36:37], v[36:37], v[44:45]
	v_pk_add_f32 v[40:41], v[32:33], v[40:41]
	v_lshlrev_b32_e32 v32, 16, v43
	v_and_b32_e32 v33, 0xffff0000, v43
	v_pk_add_f32 v[42:43], v[34:35], v[32:33]
	v_pk_mul_f32 v[32:33], v[36:37], v[36:37]
	v_pk_mul_f32 v[34:35], v[38:39], v[38:39]
	v_add_f32_e32 v32, v32, v50
	v_add_f32_e32 v32, v33, v32
	v_add_f32_e32 v32, v34, v32
	v_pk_mul_f32 v[44:45], v[40:41], v[40:41]
	v_add_f32_e32 v32, v35, v32
	v_add_f32_e32 v32, v44, v32
	v_pk_mul_f32 v[46:47], v[42:43], v[42:43]
	v_add_f32_e32 v32, v45, v32
	v_add_f32_e32 v32, v46, v32
	v_add_f32_e32 v44, v47, v32
	v_cvt_pk_bf16_f32 v32, v36, v37
	v_cvt_pk_bf16_f32 v33, v38, v39
	v_cvt_pk_bf16_f32 v34, v40, v41
	v_cvt_pk_bf16_f32 v35, v42, v43
	global_store_dwordx4 v[48:49], v[32:35], off offset:256
	ds_bpermute_b32 v32, v149, v44
	s_waitcnt lgkmcnt(0)
	v_add_f32_e32 v32, v44, v32
	ds_bpermute_b32 v33, v148, v32
	s_and_saveexec_b64 s[28:29], s[4:5]
	s_cbranch_execz .LBB0_659
	s_waitcnt lgkmcnt(0)
	v_add_f32_e32 v32, v32, v33
	global_atomic_add_f32 v[112:113], v32, off offset:576
.LBB0_659:
	s_or_b64 exec, exec, s[28:29]
	v_add_co_u32_e32 v38, vcc, 0x50000, v138
	s_mov_b64 s[28:29], 0x50000
	s_nop 0
	v_addc_co_u32_e32 v39, vcc, 0, v139, vcc
	s_waitcnt vmcnt(3)
	s_nop 1
	v_mov_b64_e32 v[34:35], v[184:185]
	v_mov_b64_e32 v[36:37], v[186:187]
	s_waitcnt lgkmcnt(0)
	v_lshl_add_u64 v[32:33], v[138:139], 0, s[28:29]
	v_lshlrev_b32_e32 v40, 16, v34
	v_and_b32_e32 v41, 0xffff0000, v34
	v_lshlrev_b32_e32 v34, 16, v35
	v_and_b32_e32 v35, 0xffff0000, v35
	v_pk_add_f32 v[30:31], v[30:31], v[34:35]
	v_lshlrev_b32_e32 v34, 16, v36
	v_and_b32_e32 v35, 0xffff0000, v36
	v_pk_add_f32 v[34:35], v[24:25], v[34:35]
	v_lshlrev_b32_e32 v24, 16, v37
	v_and_b32_e32 v25, 0xffff0000, v37
	v_pk_add_f32 v[28:29], v[28:29], v[40:41]
	v_pk_add_f32 v[36:37], v[26:27], v[24:25]
	v_cvt_pk_bf16_f32 v24, v28, v29
	v_cvt_pk_bf16_f32 v25, v30, v31
	v_cvt_pk_bf16_f32 v26, v34, v35
	v_cvt_pk_bf16_f32 v27, v36, v37
	global_store_dwordx4 v[38:39], v[24:27], off
	s_waitcnt vmcnt(2)
	s_nop 1
	v_mov_b64_e32 v[24:25], v[188:189]
	v_mov_b64_e32 v[26:27], v[190:191]
	v_pk_mul_f32 v[40:41], v[28:29], v[28:29]
	v_pk_mul_f32 v[42:43], v[30:31], v[30:31]
	v_pk_mul_f32 v[44:45], v[34:35], v[34:35]
	v_add_f32_e32 v34, v40, v41
	v_add_f32_e32 v34, v42, v34
	v_add_f32_e32 v34, v43, v34
	v_add_f32_e32 v34, v44, v34
	v_pk_mul_f32 v[46:47], v[36:37], v[36:37]
	v_add_f32_e32 v34, v45, v34
	v_add_f32_e32 v34, v46, v34
	v_add_f32_e32 v34, v47, v34
	v_lshlrev_b32_e32 v28, 16, v24
	v_and_b32_e32 v29, 0xffff0000, v24
	v_lshlrev_b32_e32 v24, 16, v25
	v_and_b32_e32 v25, 0xffff0000, v25
	v_pk_add_f32 v[22:23], v[22:23], v[24:25]
	v_lshlrev_b32_e32 v24, 16, v26
	v_and_b32_e32 v25, 0xffff0000, v26
	v_pk_add_f32 v[20:21], v[20:21], v[28:29]
	v_pk_add_f32 v[24:25], v[16:17], v[24:25]
	v_lshlrev_b32_e32 v16, 16, v27
	v_and_b32_e32 v17, 0xffff0000, v27
	v_pk_add_f32 v[26:27], v[18:19], v[16:17]
	v_pk_mul_f32 v[16:17], v[20:21], v[20:21]
	v_pk_mul_f32 v[18:19], v[22:23], v[22:23]
	v_add_f32_e32 v16, v16, v34
	v_add_f32_e32 v16, v17, v16
	v_add_f32_e32 v16, v18, v16
	v_pk_mul_f32 v[28:29], v[24:25], v[24:25]
	v_add_f32_e32 v16, v19, v16
	v_add_f32_e32 v16, v28, v16
	v_pk_mul_f32 v[30:31], v[26:27], v[26:27]
	v_add_f32_e32 v16, v29, v16
	v_add_f32_e32 v16, v30, v16
	v_add_f32_e32 v28, v31, v16
	v_cvt_pk_bf16_f32 v16, v20, v21
	v_cvt_pk_bf16_f32 v17, v22, v23
	v_cvt_pk_bf16_f32 v18, v24, v25
	v_cvt_pk_bf16_f32 v19, v26, v27
	global_store_dwordx4 v[32:33], v[16:19], off offset:256
	ds_bpermute_b32 v16, v149, v28
	s_waitcnt lgkmcnt(0)
	v_add_f32_e32 v16, v28, v16
	ds_bpermute_b32 v17, v148, v16
	s_and_saveexec_b64 s[28:29], s[4:5]
	s_cbranch_execz .LBB0_661
	s_waitcnt lgkmcnt(0)
	v_add_f32_e32 v16, v16, v17
	global_atomic_add_f32 v[112:113], v16, off offset:640
.LBB0_661:
	s_or_b64 exec, exec, s[28:29]
	v_add_co_u32_e32 v22, vcc, 0x58000, v138
	s_mov_b64 s[28:29], 0x58000
	s_nop 0
	v_addc_co_u32_e32 v23, vcc, 0, v139, vcc
	s_waitcnt vmcnt(1)
	s_nop 1
	v_mov_b64_e32 v[18:19], v[192:193]
	v_mov_b64_e32 v[20:21], v[194:195]
	s_waitcnt lgkmcnt(0)
	v_lshl_add_u64 v[16:17], v[138:139], 0, s[28:29]
	v_lshlrev_b32_e32 v24, 16, v18
	v_and_b32_e32 v25, 0xffff0000, v18
	v_lshlrev_b32_e32 v18, 16, v19
	v_and_b32_e32 v19, 0xffff0000, v19
	v_pk_add_f32 v[14:15], v[14:15], v[18:19]
	v_lshlrev_b32_e32 v18, 16, v20
	v_and_b32_e32 v19, 0xffff0000, v20
	v_pk_add_f32 v[18:19], v[8:9], v[18:19]
	v_lshlrev_b32_e32 v8, 16, v21
	v_and_b32_e32 v9, 0xffff0000, v21
	v_pk_add_f32 v[12:13], v[12:13], v[24:25]
	v_pk_add_f32 v[20:21], v[10:11], v[8:9]
	v_cvt_pk_bf16_f32 v8, v12, v13
	v_cvt_pk_bf16_f32 v9, v14, v15
	v_cvt_pk_bf16_f32 v10, v18, v19
	v_cvt_pk_bf16_f32 v11, v20, v21
	global_store_dwordx4 v[22:23], v[8:11], off
	s_waitcnt vmcnt(0)
	s_nop 1
	v_mov_b64_e32 v[8:9], v[196:197]
	v_mov_b64_e32 v[10:11], v[198:199]
	v_pk_mul_f32 v[24:25], v[12:13], v[12:13]
	v_pk_mul_f32 v[26:27], v[14:15], v[14:15]
	v_pk_mul_f32 v[28:29], v[18:19], v[18:19]
	v_add_f32_e32 v18, v24, v25
	v_add_f32_e32 v18, v26, v18
	v_add_f32_e32 v18, v27, v18
	v_add_f32_e32 v18, v28, v18
	v_pk_mul_f32 v[30:31], v[20:21], v[20:21]
	v_add_f32_e32 v18, v29, v18
	v_add_f32_e32 v18, v30, v18
	v_add_f32_e32 v18, v31, v18
	v_lshlrev_b32_e32 v12, 16, v8
	v_and_b32_e32 v13, 0xffff0000, v8
	v_lshlrev_b32_e32 v8, 16, v9
	v_and_b32_e32 v9, 0xffff0000, v9
	v_pk_add_f32 v[6:7], v[6:7], v[8:9]
	v_lshlrev_b32_e32 v8, 16, v10
	v_and_b32_e32 v9, 0xffff0000, v10
	v_pk_add_f32 v[4:5], v[4:5], v[12:13]
	v_pk_add_f32 v[8:9], v[0:1], v[8:9]
	v_lshlrev_b32_e32 v0, 16, v11
	v_and_b32_e32 v1, 0xffff0000, v11
	v_pk_add_f32 v[10:11], v[2:3], v[0:1]
	v_pk_mul_f32 v[0:1], v[4:5], v[4:5]
	v_pk_mul_f32 v[2:3], v[6:7], v[6:7]
	v_add_f32_e32 v0, v0, v18
	v_add_f32_e32 v0, v1, v0
	v_add_f32_e32 v0, v2, v0
	v_pk_mul_f32 v[12:13], v[8:9], v[8:9]
	v_add_f32_e32 v0, v3, v0
	v_add_f32_e32 v0, v12, v0
	v_pk_mul_f32 v[14:15], v[10:11], v[10:11]
	v_add_f32_e32 v0, v13, v0
	v_add_f32_e32 v0, v14, v0
	v_add_f32_e32 v12, v15, v0
	v_cvt_pk_bf16_f32 v0, v4, v5
	v_cvt_pk_bf16_f32 v1, v6, v7
	v_cvt_pk_bf16_f32 v2, v8, v9
	v_cvt_pk_bf16_f32 v3, v10, v11
	global_store_dwordx4 v[16:17], v[0:3], off offset:256
	ds_bpermute_b32 v0, v149, v12
	s_waitcnt lgkmcnt(0)
	v_add_f32_e32 v0, v12, v0
	ds_bpermute_b32 v1, v148, v0
	s_and_saveexec_b64 s[28:29], s[4:5]
	s_cbranch_execz .LBB0_663
	s_waitcnt lgkmcnt(0)
	v_add_f32_e32 v0, v0, v1
	global_atomic_add_f32 v[112:113], v0, off offset:704

.LBB0_757:
	v_lshl_or_b32 v152, s12, 7, v222
	v_cmp_gt_i32_e32 vcc, s35, v229
	s_add_i32 s24, s35, -16
	v_lshlrev_b32_e32 v153, 1, v152
	s_and_b64 s[50:51], s[84:85], vcc
	v_add_u32_e32 v155, s94, v229
	v_xor_b32_e32 v159, 0x80000000, v91
	v_xor_b32_e32 v158, 0x80000000, v90
	v_xor_b32_e32 v157, 0x80000000, v83
	v_xor_b32_e32 v156, 0x80000000, v82
	s_and_saveexec_b64 s[12:13], s[50:51]
	s_cbranch_execz .LBB0_759
	s_cmp_ge_i32 s25, s24
	v_pk_fma_f32 v[144:145], v[80:81], v[200:201], v[144:145]
	s_cselect_b64 s[14:15], -1, 0
	v_pk_add_f32 v[144:145], v[84:85], v[144:145]
	v_pk_fma_f32 v[148:149], v[88:89], v[204:205], v[148:149]
	v_pk_fma_f32 v[146:147], v[82:83], v[202:203], v[146:147]
	v_pk_fma_f32 v[150:151], v[90:91], v[206:207], v[150:151]
	v_pk_add_f32 v[148:149], v[92:93], v[148:149]
	v_pk_add_f32 v[146:147], v[86:87], v[146:147]
	v_pk_add_f32 v[150:151], v[94:95], v[150:151]
	s_mov_b32 s16, 0x3f35f0e3
	s_mov_b32 s18, 0xbe11a98e
	s_mov_b32 s28, 0x3e027906
	s_cmp_eq_u64 s[14:15], 0
	s_cbranch_scc1 .Lffe_759
	v_cmp_eq_u32_e32 vcc, s37, v229
	s_nop 1
	s_and_b64 vcc, s[14:15], vcc
	v_pk_fma_f32 v[200:201], v[80:81], v[200:201], v[144:145] neg_lo:[1,0,0] neg_hi:[1,0,0]
	s_nop 0
	v_cndmask_b32_e32 v145, v145, v201, vcc
	v_cndmask_b32_e32 v144, v144, v200, vcc
	v_pk_fma_f32 v[204:205], v[88:89], v[204:205], v[148:149] neg_lo:[1,0,0] neg_hi:[1,0,0]
	v_pk_fma_f32 v[202:203], v[156:157], v[202:203], v[146:147]
	v_pk_fma_f32 v[206:207], v[158:159], v[206:207], v[150:151]
	v_cndmask_b32_e32 v149, v149, v205, vcc
	v_cndmask_b32_e32 v148, v148, v204, vcc
	v_cndmask_b32_e32 v146, v146, v202, vcc
	v_cndmask_b32_e32 v151, v151, v207, vcc
	v_cndmask_b32_e32 v150, v150, v206, vcc
	v_cndmask_b32_e32 v147, v147, v203, vcc
.Lffe_759:
	s_mov_b32 s14, 0xbf3a00e3
	v_fma_f32 v154, |v144|, s74, 1.0
	v_fma_f32 v201, |v145|, s74, 1.0
	v_mov_b64_e32 v[204:205], s[14:15]
	v_rcp_f32_e32 v200, v154
	v_rcp_f32_e32 v201, v201
	s_mov_b32 s14, 0x3f07dc22
	v_mul_f32_e32 v154, v144, v144
	v_pk_fma_f32 v[206:207], v[200:201], s[14:15], v[204:205] op_sel_hi:[1,0,0]
	v_mul_f32_e32 v154, 0xbf38aa3b, v154
	v_pk_fma_f32 v[206:207], v[200:201], v[206:207], s[16:17] op_sel_hi:[1,1,0]
	v_exp_f32_e32 v202, v154
	v_pk_fma_f32 v[206:207], v[200:201], v[206:207], s[18:19] op_sel_hi:[1,1,0]
	v_mul_f32_e32 v154, v145, v145
	v_pk_fma_f32 v[206:207], v[200:201], v[206:207], s[28:29] op_sel_hi:[1,1,0]
	v_mul_f32_e32 v154, 0xbf38aa3b, v154
	v_exp_f32_e32 v203, v154
	v_pk_mul_f32 v[200:201], v[200:201], v[206:207]
	v_cmp_gt_f32_e32 vcc, 0, v145
	v_pk_mul_f32 v[200:201], v[202:203], v[200:201]
	s_nop 0
	v_pk_mul_f32 v[202:203], v[144:145], v[200:201]
	v_pk_fma_f32 v[200:201], v[144:145], v[200:201], v[144:145] neg_lo:[1,0,0] neg_hi:[1,0,0]
	s_nop 0
	v_cndmask_b32_e32 v145, v201, v203, vcc
	v_cmp_gt_f32_e32 vcc, 0, v144
	s_nop 1
	v_cndmask_b32_e32 v144, v200, v202, vcc
	v_pk_mul_f32 v[144:145], v[148:149], v[144:145]
	v_cmp_gt_f32_e32 vcc, 0, v147
	v_cvt_pk_bf16_f32 v144, v144, v145
	v_fma_f32 v145, |v146|, s74, 1.0
	v_rcp_f32_e32 v148, v145
	v_fma_f32 v145, |v147|, s74, 1.0
	v_rcp_f32_e32 v149, v145
	v_mul_f32_e32 v145, v146, v146
	v_pk_fma_f32 v[202:203], v[148:149], s[14:15], v[204:205] op_sel_hi:[1,0,0]
	v_mul_f32_e32 v145, 0xbf38aa3b, v145
	v_pk_fma_f32 v[202:203], v[148:149], v[202:203], s[16:17] op_sel_hi:[1,1,0]
	v_exp_f32_e32 v200, v145
	v_pk_fma_f32 v[202:203], v[148:149], v[202:203], s[18:19] op_sel_hi:[1,1,0]
	v_mul_f32_e32 v145, v147, v147
	v_pk_fma_f32 v[202:203], v[148:149], v[202:203], s[28:29] op_sel_hi:[1,1,0]
	v_mul_f32_e32 v145, 0xbf38aa3b, v145
	v_exp_f32_e32 v201, v145
	v_pk_mul_f32 v[148:149], v[148:149], v[202:203]
	s_movk_i32 s14, 0x1600
	v_pk_mul_f32 v[148:149], v[200:201], v[148:149]
	s_nop 0
	v_pk_mul_f32 v[200:201], v[146:147], v[148:149]
	v_pk_fma_f32 v[148:149], v[146:147], v[148:149], v[146:147] neg_lo:[1,0,0] neg_hi:[1,0,0]
	s_nop 0
	v_cndmask_b32_e32 v147, v149, v201, vcc
	v_cmp_gt_f32_e32 vcc, 0, v146
	s_nop 1
	v_cndmask_b32_e32 v146, v148, v200, vcc
	v_pk_mul_f32 v[146:147], v[150:151], v[146:147]
	s_nop 0
	v_cvt_pk_bf16_f32 v145, v146, v147
	v_mad_u32_u24 v146, v155, s14, v153
	global_store_dwordx2 v146, v[144:145], s[26:27]

.Lffe_765:
	s_mov_b32 s16, 0xbf3a00e3
	v_fma_f32 v144, |v136|, s74, 1.0
	v_fma_f32 v147, |v137|, s74, 1.0
	v_mov_b64_e32 v[150:151], s[16:17]
	v_rcp_f32_e32 v146, v144
	v_rcp_f32_e32 v147, v147
	s_mov_b32 s16, 0x3f07dc22
	v_mul_f32_e32 v144, v136, v136
	v_pk_fma_f32 v[208:209], v[146:147], s[16:17], v[150:151] op_sel_hi:[1,0,0]
	v_mul_f32_e32 v144, 0xbf38aa3b, v144
	v_pk_fma_f32 v[208:209], v[146:147], v[208:209], s[18:19] op_sel_hi:[1,1,0]
	v_exp_f32_e32 v148, v144
	v_pk_fma_f32 v[208:209], v[146:147], v[208:209], s[28:29] op_sel_hi:[1,1,0]
	v_mul_f32_e32 v144, v137, v137
	v_pk_fma_f32 v[208:209], v[146:147], v[208:209], s[54:55] op_sel_hi:[1,1,0]
	v_mul_f32_e32 v144, 0xbf38aa3b, v144
	v_exp_f32_e32 v149, v144
	v_pk_mul_f32 v[146:147], v[146:147], v[208:209]
	v_cmp_gt_f32_e32 vcc, 0, v137
	v_pk_mul_f32 v[146:147], v[148:149], v[146:147]
	s_nop 0
	v_pk_mul_f32 v[148:149], v[136:137], v[146:147]
	v_pk_fma_f32 v[146:147], v[136:137], v[146:147], v[136:137] neg_lo:[1,0,0] neg_hi:[1,0,0]
	s_nop 0
	v_cndmask_b32_e32 v137, v147, v149, vcc
	v_cmp_gt_f32_e32 vcc, 0, v136
	s_nop 1
	v_cndmask_b32_e32 v136, v146, v148, vcc
	v_pk_mul_f32 v[136:137], v[140:141], v[136:137]
	v_cmp_gt_f32_e32 vcc, 0, v139
	v_cvt_pk_bf16_f32 v136, v136, v137
	v_fma_f32 v137, |v138|, s74, 1.0
	v_rcp_f32_e32 v140, v137
	v_fma_f32 v137, |v139|, s74, 1.0
	v_rcp_f32_e32 v141, v137
	v_mul_f32_e32 v137, v138, v138
	v_pk_fma_f32 v[148:149], v[140:141], s[16:17], v[150:151] op_sel_hi:[1,0,0]
	v_mul_f32_e32 v137, 0xbf38aa3b, v137
	v_pk_fma_f32 v[148:149], v[140:141], v[148:149], s[18:19] op_sel_hi:[1,1,0]
	v_exp_f32_e32 v146, v137
	v_pk_fma_f32 v[148:149], v[140:141], v[148:149], s[28:29] op_sel_hi:[1,1,0]
	v_mul_f32_e32 v137, v139, v139
	v_pk_fma_f32 v[148:149], v[140:141], v[148:149], s[54:55] op_sel_hi:[1,1,0]
	v_mul_f32_e32 v137, 0xbf38aa3b, v137
	v_exp_f32_e32 v147, v137
	v_pk_mul_f32 v[140:141], v[140:141], v[148:149]
	s_movk_i32 s16, 0x1600
	v_pk_mul_f32 v[140:141], v[146:147], v[140:141]
	s_nop 0
	v_pk_mul_f32 v[146:147], v[138:139], v[140:141]
	v_pk_fma_f32 v[140:141], v[138:139], v[140:141], v[138:139] neg_lo:[1,0,0] neg_hi:[1,0,0]
	s_nop 0
	v_cndmask_b32_e32 v139, v141, v147, vcc
	v_cmp_gt_f32_e32 vcc, 0, v138
	s_nop 1
	v_cndmask_b32_e32 v138, v140, v146, vcc
	v_pk_mul_f32 v[138:139], v[142:143], v[138:139]
	s_nop 0
	v_cvt_pk_bf16_f32 v137, v138, v139
	v_mad_u32_u24 v138, v145, s16, v153
	global_store_dwordx2 v138, v[136:137], s[26:27]

.Lffe_771:
	s_mov_b32 s18, 0xbf3a00e3
	v_fma_f32 v136, |v128|, s74, 1.0
	v_fma_f32 v137, |v129|, s74, 1.0
	v_mov_b64_e32 v[140:141], s[18:19]
	v_rcp_f32_e32 v136, v136
	v_rcp_f32_e32 v137, v137
	s_mov_b32 s18, 0x3f07dc22
	v_mul_f32_e32 v138, v128, v128
	v_pk_fma_f32 v[142:143], v[136:137], s[18:19], v[140:141] op_sel_hi:[1,0,0]
	v_mul_f32_e32 v139, v129, v129
	v_pk_fma_f32 v[142:143], v[136:137], v[142:143], s[60:61] op_sel_hi:[1,1,0]
	v_mul_f32_e32 v138, 0xbf38aa3b, v138
	v_pk_fma_f32 v[142:143], v[136:137], v[142:143], s[28:29] op_sel_hi:[1,1,0]
	v_mul_f32_e32 v139, 0xbf38aa3b, v139
	v_pk_fma_f32 v[142:143], v[136:137], v[142:143], s[64:65] op_sel_hi:[1,1,0]
	v_exp_f32_e32 v138, v138
	v_exp_f32_e32 v139, v139
	v_pk_mul_f32 v[136:137], v[136:137], v[142:143]
	v_cmp_gt_f32_e32 vcc, 0, v129
	v_pk_mul_f32 v[136:137], v[138:139], v[136:137]
	s_nop 0
	v_pk_mul_f32 v[138:139], v[128:129], v[136:137]
	v_pk_fma_f32 v[136:137], v[128:129], v[136:137], v[128:129] neg_lo:[1,0,0] neg_hi:[1,0,0]
	s_nop 0
	v_cndmask_b32_e32 v129, v137, v139, vcc
	v_cmp_gt_f32_e32 vcc, 0, v128
	s_nop 1
	v_cndmask_b32_e32 v128, v136, v138, vcc
	v_pk_mul_f32 v[128:129], v[132:133], v[128:129]
	v_cmp_gt_f32_e32 vcc, 0, v131
	v_cvt_pk_bf16_f32 v128, v128, v129
	v_fma_f32 v129, |v130|, s74, 1.0
	v_rcp_f32_e32 v132, v129
	v_fma_f32 v129, |v131|, s74, 1.0
	v_rcp_f32_e32 v133, v129
	v_mul_f32_e32 v129, v130, v130
	v_pk_fma_f32 v[138:139], v[132:133], s[18:19], v[140:141] op_sel_hi:[1,0,0]
	v_mul_f32_e32 v129, 0xbf38aa3b, v129
	v_pk_fma_f32 v[138:139], v[132:133], v[138:139], s[60:61] op_sel_hi:[1,1,0]
	v_exp_f32_e32 v136, v129
	v_pk_fma_f32 v[138:139], v[132:133], v[138:139], s[28:29] op_sel_hi:[1,1,0]
	v_mul_f32_e32 v129, v131, v131
	v_pk_fma_f32 v[138:139], v[132:133], v[138:139], s[64:65] op_sel_hi:[1,1,0]
	v_mul_f32_e32 v129, 0xbf38aa3b, v129
	v_exp_f32_e32 v137, v129
	v_pk_mul_f32 v[132:133], v[132:133], v[138:139]
	s_movk_i32 s18, 0x1600
	v_pk_mul_f32 v[132:133], v[136:137], v[132:133]
	s_nop 0
	v_pk_mul_f32 v[136:137], v[130:131], v[132:133]
	v_pk_fma_f32 v[132:133], v[130:131], v[132:133], v[130:131] neg_lo:[1,0,0] neg_hi:[1,0,0]
	s_nop 0
	v_cndmask_b32_e32 v131, v133, v137, vcc
	v_cmp_gt_f32_e32 vcc, 0, v130
	s_nop 1
	v_cndmask_b32_e32 v130, v132, v136, vcc
	v_pk_mul_f32 v[130:131], v[134:135], v[130:131]
	s_nop 0
	v_cvt_pk_bf16_f32 v129, v130, v131
	v_mad_u32_u24 v130, v210, s18, v153
	global_store_dwordx2 v130, v[128:129], s[26:27]

.Lffe_777:
	s_mov_b32 s18, 0xbf3a00e3
	v_fma_f32 v136, |v128|, s74, 1.0
	v_fma_f32 v137, |v129|, s74, 1.0
	v_mov_b64_e32 v[140:141], s[18:19]
	v_rcp_f32_e32 v136, v136
	v_rcp_f32_e32 v137, v137
	s_mov_b32 s18, 0x3f07dc22
	v_mul_f32_e32 v138, v128, v128
	v_pk_fma_f32 v[142:143], v[136:137], s[18:19], v[140:141] op_sel_hi:[1,0,0]
	v_mul_f32_e32 v139, v129, v129
	v_pk_fma_f32 v[142:143], v[136:137], v[142:143], s[60:61] op_sel_hi:[1,1,0]
	v_mul_f32_e32 v138, 0xbf38aa3b, v138
	v_pk_fma_f32 v[142:143], v[136:137], v[142:143], s[28:29] op_sel_hi:[1,1,0]
	v_mul_f32_e32 v139, 0xbf38aa3b, v139
	v_pk_fma_f32 v[142:143], v[136:137], v[142:143], s[64:65] op_sel_hi:[1,1,0]
	v_exp_f32_e32 v138, v138
	v_exp_f32_e32 v139, v139
	v_pk_mul_f32 v[136:137], v[136:137], v[142:143]
	v_cmp_gt_f32_e32 vcc, 0, v129
	v_pk_mul_f32 v[136:137], v[138:139], v[136:137]
	s_nop 0
	v_pk_mul_f32 v[138:139], v[128:129], v[136:137]
	v_pk_fma_f32 v[136:137], v[128:129], v[136:137], v[128:129] neg_lo:[1,0,0] neg_hi:[1,0,0]
	s_nop 0
	v_cndmask_b32_e32 v129, v137, v139, vcc
	v_cmp_gt_f32_e32 vcc, 0, v128
	s_nop 1
	v_cndmask_b32_e32 v128, v136, v138, vcc
	v_pk_mul_f32 v[128:129], v[132:133], v[128:129]
	v_cmp_gt_f32_e32 vcc, 0, v131
	v_cvt_pk_bf16_f32 v128, v128, v129
	v_fma_f32 v129, |v130|, s74, 1.0
	v_rcp_f32_e32 v132, v129
	v_fma_f32 v129, |v131|, s74, 1.0
	v_rcp_f32_e32 v133, v129
	v_mul_f32_e32 v129, v130, v130
	v_pk_fma_f32 v[138:139], v[132:133], s[18:19], v[140:141] op_sel_hi:[1,0,0]
	v_mul_f32_e32 v129, 0xbf38aa3b, v129
	v_pk_fma_f32 v[138:139], v[132:133], v[138:139], s[60:61] op_sel_hi:[1,1,0]
	v_exp_f32_e32 v136, v129
	v_pk_fma_f32 v[138:139], v[132:133], v[138:139], s[28:29] op_sel_hi:[1,1,0]
	v_mul_f32_e32 v129, v131, v131
	v_pk_fma_f32 v[138:139], v[132:133], v[138:139], s[64:65] op_sel_hi:[1,1,0]
	v_mul_f32_e32 v129, 0xbf38aa3b, v129
	v_exp_f32_e32 v137, v129
	v_pk_mul_f32 v[132:133], v[132:133], v[138:139]
	s_movk_i32 s18, 0x1600
	v_pk_mul_f32 v[132:133], v[136:137], v[132:133]
	s_nop 0
	v_pk_mul_f32 v[136:137], v[130:131], v[132:133]
	v_pk_fma_f32 v[132:133], v[130:131], v[132:133], v[130:131] neg_lo:[1,0,0] neg_hi:[1,0,0]
	s_nop 0
	v_cndmask_b32_e32 v131, v133, v137, vcc
	v_cmp_gt_f32_e32 vcc, 0, v130
	s_nop 1
	v_cndmask_b32_e32 v130, v132, v136, vcc
	v_pk_mul_f32 v[130:131], v[134:135], v[130:131]
	s_nop 0
	v_cvt_pk_bf16_f32 v129, v130, v131
	v_mad_u32_u24 v130, v200, s18, v153
	global_store_dwordx2 v130, v[128:129], s[26:27]

.Lffe_783:
	s_mov_b32 s18, 0xbf3a00e3
	v_fma_f32 v104, |v96|, s74, 1.0
	v_fma_f32 v107, |v97|, s74, 1.0
	v_mov_b64_e32 v[114:115], s[18:19]
	v_rcp_f32_e32 v106, v104
	v_rcp_f32_e32 v107, v107
	s_mov_b32 s18, 0x3f07dc22
	v_mul_f32_e32 v104, v96, v96
	v_pk_fma_f32 v[136:137], v[106:107], s[18:19], v[114:115] op_sel_hi:[1,0,0]
	v_mul_f32_e32 v104, 0xbf38aa3b, v104
	v_pk_fma_f32 v[136:137], v[106:107], v[136:137], s[60:61] op_sel_hi:[1,1,0]
	v_exp_f32_e32 v112, v104
	v_pk_fma_f32 v[136:137], v[106:107], v[136:137], s[28:29] op_sel_hi:[1,1,0]
	v_mul_f32_e32 v104, v97, v97
	v_pk_fma_f32 v[136:137], v[106:107], v[136:137], s[64:65] op_sel_hi:[1,1,0]
	v_mul_f32_e32 v104, 0xbf38aa3b, v104
	v_exp_f32_e32 v113, v104
	v_pk_mul_f32 v[106:107], v[106:107], v[136:137]
	v_cmp_gt_f32_e32 vcc, 0, v97
	v_pk_mul_f32 v[106:107], v[112:113], v[106:107]
	s_nop 0
	v_pk_mul_f32 v[112:113], v[96:97], v[106:107]
	v_pk_fma_f32 v[106:107], v[96:97], v[106:107], v[96:97] neg_lo:[1,0,0] neg_hi:[1,0,0]
	s_nop 0
	v_cndmask_b32_e32 v97, v107, v113, vcc
	v_cmp_gt_f32_e32 vcc, 0, v96
	s_nop 1
	v_cndmask_b32_e32 v96, v106, v112, vcc
	v_pk_mul_f32 v[96:97], v[100:101], v[96:97]
	v_cmp_gt_f32_e32 vcc, 0, v99
	v_cvt_pk_bf16_f32 v96, v96, v97
	v_fma_f32 v97, |v98|, s74, 1.0
	v_rcp_f32_e32 v100, v97
	v_fma_f32 v97, |v99|, s74, 1.0
	v_rcp_f32_e32 v101, v97
	v_mul_f32_e32 v97, v98, v98
	v_pk_fma_f32 v[112:113], v[100:101], s[18:19], v[114:115] op_sel_hi:[1,0,0]
	v_mul_f32_e32 v97, 0xbf38aa3b, v97
	v_pk_fma_f32 v[112:113], v[100:101], v[112:113], s[60:61] op_sel_hi:[1,1,0]
	v_exp_f32_e32 v106, v97
	v_pk_fma_f32 v[112:113], v[100:101], v[112:113], s[28:29] op_sel_hi:[1,1,0]
	v_mul_f32_e32 v97, v99, v99
	v_pk_fma_f32 v[112:113], v[100:101], v[112:113], s[64:65] op_sel_hi:[1,1,0]
	v_mul_f32_e32 v97, 0xbf38aa3b, v97
	v_exp_f32_e32 v107, v97
	v_pk_mul_f32 v[100:101], v[100:101], v[112:113]
	s_movk_i32 s18, 0x1600
	v_pk_mul_f32 v[100:101], v[106:107], v[100:101]
	s_nop 0
	v_pk_mul_f32 v[106:107], v[98:99], v[100:101]
	v_pk_fma_f32 v[100:101], v[98:99], v[100:101], v[98:99] neg_lo:[1,0,0] neg_hi:[1,0,0]
	s_nop 0
	v_cndmask_b32_e32 v99, v101, v107, vcc
	v_cmp_gt_f32_e32 vcc, 0, v98
	s_nop 1
	v_cndmask_b32_e32 v98, v100, v106, vcc
	v_pk_mul_f32 v[98:99], v[102:103], v[98:99]
	s_nop 0
	v_cvt_pk_bf16_f32 v97, v98, v99
	v_mad_u32_u24 v98, v105, s18, v153
	global_store_dwordx2 v98, v[96:97], s[26:27]

.Lffe_789:
	v_fma_f32 v96, |v72|, s74, 1.0
	v_fma_f32 v99, |v73|, s74, 1.0
	v_rcp_f32_e32 v98, v96
	v_rcp_f32_e32 v99, v99
	v_mul_f32_e32 v96, v72, v72
	v_pk_fma_f32 v[142:143], v[98:99], s[64:65], v[102:103] op_sel_hi:[1,0,0]
	v_mul_f32_e32 v96, 0xbf38aa3b, v96
	v_pk_fma_f32 v[142:143], v[98:99], v[142:143], s[66:67] op_sel_hi:[1,1,0]
	v_exp_f32_e32 v100, v96
	v_pk_fma_f32 v[142:143], v[98:99], v[142:143], s[28:29] op_sel_hi:[1,1,0]
	v_mul_f32_e32 v96, v73, v73
	v_pk_fma_f32 v[142:143], v[98:99], v[142:143], s[76:77] op_sel_hi:[1,1,0]
	v_mul_f32_e32 v96, 0xbf38aa3b, v96
	v_exp_f32_e32 v101, v96
	v_pk_mul_f32 v[98:99], v[98:99], v[142:143]
	v_cmp_gt_f32_e32 vcc, 0, v73
	v_pk_mul_f32 v[98:99], v[100:101], v[98:99]
	s_nop 0
	v_pk_mul_f32 v[100:101], v[72:73], v[98:99]
	v_pk_fma_f32 v[98:99], v[72:73], v[98:99], v[72:73] neg_lo:[1,0,0] neg_hi:[1,0,0]
	s_nop 0
	v_cndmask_b32_e32 v73, v99, v101, vcc
	v_cmp_gt_f32_e32 vcc, 0, v72
	s_nop 1
	v_cndmask_b32_e32 v72, v98, v100, vcc
	v_pk_mul_f32 v[72:73], v[76:77], v[72:73]
	v_cmp_gt_f32_e32 vcc, 0, v75
	v_cvt_pk_bf16_f32 v72, v72, v73
	v_fma_f32 v73, |v74|, s74, 1.0
	v_rcp_f32_e32 v76, v73
	v_fma_f32 v73, |v75|, s74, 1.0
	v_rcp_f32_e32 v77, v73
	v_mul_f32_e32 v73, v74, v74
	v_pk_fma_f32 v[100:101], v[76:77], s[64:65], v[102:103] op_sel_hi:[1,0,0]
	v_mul_f32_e32 v73, 0xbf38aa3b, v73
	v_pk_fma_f32 v[100:101], v[76:77], v[100:101], s[66:67] op_sel_hi:[1,1,0]
	v_exp_f32_e32 v98, v73
	v_pk_fma_f32 v[100:101], v[76:77], v[100:101], s[28:29] op_sel_hi:[1,1,0]
	v_mul_f32_e32 v73, v75, v75
	v_pk_fma_f32 v[100:101], v[76:77], v[100:101], s[76:77] op_sel_hi:[1,1,0]
	v_mul_f32_e32 v73, 0xbf38aa3b, v73
	v_exp_f32_e32 v99, v73
	v_pk_mul_f32 v[76:77], v[76:77], v[100:101]
	s_movk_i32 s64, 0x1600
	v_pk_mul_f32 v[76:77], v[98:99], v[76:77]
	s_nop 0
	v_pk_mul_f32 v[98:99], v[74:75], v[76:77]
	v_pk_fma_f32 v[76:77], v[74:75], v[76:77], v[74:75] neg_lo:[1,0,0] neg_hi:[1,0,0]
	s_nop 0
	v_cndmask_b32_e32 v75, v77, v99, vcc
	v_cmp_gt_f32_e32 vcc, 0, v74
	s_nop 1
	v_cndmask_b32_e32 v74, v76, v98, vcc
	v_pk_mul_f32 v[74:75], v[78:79], v[74:75]
	s_nop 0
	v_cvt_pk_bf16_f32 v73, v74, v75
	v_mad_u32_u24 v74, v97, s64, v153
	global_store_dwordx2 v74, v[72:73], s[26:27]

.Lffe_795:
	v_fma_f32 v72, |v64|, s74, 1.0
	v_fma_f32 v73, |v65|, s74, 1.0
	v_rcp_f32_e32 v72, v72
	v_rcp_f32_e32 v73, v73
	s_mov_b32 s92, 0x3f35f0e3
	v_pk_fma_f32 v[78:79], v[72:73], s[66:67], v[76:77] op_sel_hi:[1,0,0]
	v_mul_f32_e32 v74, v64, v64
	v_pk_fma_f32 v[78:79], v[72:73], v[78:79], s[92:93] op_sel_hi:[1,1,0]
	v_mul_f32_e32 v75, v65, v65
	v_pk_fma_f32 v[78:79], v[72:73], v[78:79], s[28:29] op_sel_hi:[1,1,0]
	v_mul_f32_e32 v74, 0xbf38aa3b, v74
	v_pk_fma_f32 v[78:79], v[72:73], v[78:79], s[76:77] op_sel_hi:[1,1,0]
	v_mul_f32_e32 v75, 0xbf38aa3b, v75
	v_exp_f32_e32 v74, v74
	v_exp_f32_e32 v75, v75
	v_pk_mul_f32 v[72:73], v[72:73], v[78:79]
	v_cmp_gt_f32_e32 vcc, 0, v65
	v_pk_mul_f32 v[72:73], v[74:75], v[72:73]
	s_nop 0
	v_pk_mul_f32 v[74:75], v[64:65], v[72:73]
	v_pk_fma_f32 v[72:73], v[64:65], v[72:73], v[64:65] neg_lo:[1,0,0] neg_hi:[1,0,0]
	s_nop 0
	v_cndmask_b32_e32 v65, v73, v75, vcc
	v_cmp_gt_f32_e32 vcc, 0, v64
	s_nop 1
	v_cndmask_b32_e32 v64, v72, v74, vcc
	v_pk_mul_f32 v[64:65], v[68:69], v[64:65]
	v_cmp_gt_f32_e32 vcc, 0, v67
	v_cvt_pk_bf16_f32 v64, v64, v65
	v_fma_f32 v65, |v66|, s74, 1.0
	v_rcp_f32_e32 v68, v65
	v_fma_f32 v65, |v67|, s74, 1.0
	v_rcp_f32_e32 v69, v65
	v_mul_f32_e32 v65, v66, v66
	v_pk_fma_f32 v[74:75], v[68:69], s[66:67], v[76:77] op_sel_hi:[1,0,0]
	v_mul_f32_e32 v65, 0xbf38aa3b, v65
	v_pk_fma_f32 v[74:75], v[68:69], v[74:75], s[92:93] op_sel_hi:[1,1,0]
	v_exp_f32_e32 v72, v65
	v_pk_fma_f32 v[74:75], v[68:69], v[74:75], s[28:29] op_sel_hi:[1,1,0]
	v_mul_f32_e32 v65, v67, v67
	v_pk_fma_f32 v[74:75], v[68:69], v[74:75], s[76:77] op_sel_hi:[1,1,0]
	v_mul_f32_e32 v65, 0xbf38aa3b, v65
	v_exp_f32_e32 v73, v65
	v_pk_mul_f32 v[68:69], v[68:69], v[74:75]
	s_movk_i32 s66, 0x1600
	v_pk_mul_f32 v[68:69], v[72:73], v[68:69]
	s_nop 0
	v_pk_mul_f32 v[72:73], v[66:67], v[68:69]
	v_pk_fma_f32 v[68:69], v[66:67], v[68:69], v[66:67] neg_lo:[1,0,0] neg_hi:[1,0,0]
	s_nop 0
	v_cndmask_b32_e32 v67, v69, v73, vcc
	v_cmp_gt_f32_e32 vcc, 0, v66
	s_nop 1
	v_cndmask_b32_e32 v66, v68, v72, vcc
	v_pk_mul_f32 v[66:67], v[70:71], v[66:67]
	s_nop 0
	v_cvt_pk_bf16_f32 v65, v66, v67
	v_mad_u32_u24 v66, v146, s66, v153
	global_store_dwordx2 v66, v[64:65], s[26:27]

.Lffe_801:
	s_mov_b32 s70, 0xbf3a00e3
	v_fma_f32 v72, |v64|, s74, 1.0
	v_fma_f32 v73, |v65|, s74, 1.0
	v_mov_b64_e32 v[76:77], s[70:71]
	v_rcp_f32_e32 v72, v72
	v_rcp_f32_e32 v73, v73
	s_mov_b32 s70, 0x3f07dc22
	v_mul_f32_e32 v74, v64, v64
	v_pk_fma_f32 v[78:79], v[72:73], s[70:71], v[76:77] op_sel_hi:[1,0,0]
	v_mul_f32_e32 v75, v65, v65
	v_pk_fma_f32 v[78:79], v[72:73], v[78:79], s[28:29] op_sel_hi:[1,1,0]
	v_mul_f32_e32 v74, 0xbf38aa3b, v74
	v_pk_fma_f32 v[78:79], v[72:73], v[78:79], s[76:77] op_sel_hi:[1,1,0]
	v_mul_f32_e32 v75, 0xbf38aa3b, v75
	v_pk_fma_f32 v[78:79], v[72:73], v[78:79], s[8:9] op_sel_hi:[1,1,0]
	v_exp_f32_e32 v74, v74
	v_exp_f32_e32 v75, v75
	v_pk_mul_f32 v[72:73], v[72:73], v[78:79]
	v_cmp_gt_f32_e32 vcc, 0, v65
	v_pk_mul_f32 v[72:73], v[74:75], v[72:73]
	s_nop 0
	v_pk_mul_f32 v[74:75], v[64:65], v[72:73]
	v_pk_fma_f32 v[72:73], v[64:65], v[72:73], v[64:65] neg_lo:[1,0,0] neg_hi:[1,0,0]
	s_nop 0
	v_cndmask_b32_e32 v65, v73, v75, vcc
	v_cmp_gt_f32_e32 vcc, 0, v64
	s_nop 1
	v_cndmask_b32_e32 v64, v72, v74, vcc
	v_pk_mul_f32 v[64:65], v[68:69], v[64:65]
	v_cmp_gt_f32_e32 vcc, 0, v67
	v_cvt_pk_bf16_f32 v64, v64, v65
	v_fma_f32 v65, |v66|, s74, 1.0
	v_rcp_f32_e32 v68, v65
	v_fma_f32 v65, |v67|, s74, 1.0
	v_rcp_f32_e32 v69, v65
	v_mul_f32_e32 v65, v66, v66
	v_pk_fma_f32 v[74:75], v[68:69], s[70:71], v[76:77] op_sel_hi:[1,0,0]
	v_mul_f32_e32 v65, 0xbf38aa3b, v65
	v_pk_fma_f32 v[74:75], v[68:69], v[74:75], s[28:29] op_sel_hi:[1,1,0]
	v_exp_f32_e32 v72, v65
	v_pk_fma_f32 v[74:75], v[68:69], v[74:75], s[76:77] op_sel_hi:[1,1,0]
	v_mul_f32_e32 v65, v67, v67
	v_pk_fma_f32 v[74:75], v[68:69], v[74:75], s[8:9] op_sel_hi:[1,1,0]
	v_mul_f32_e32 v65, 0xbf38aa3b, v65
	v_exp_f32_e32 v73, v65
	v_pk_mul_f32 v[68:69], v[68:69], v[74:75]
	s_movk_i32 s70, 0x1600
	v_pk_mul_f32 v[68:69], v[72:73], v[68:69]
	v_readlane_b32 s71, v242, 1
	v_pk_mul_f32 v[72:73], v[66:67], v[68:69]
	v_pk_fma_f32 v[68:69], v[66:67], v[68:69], v[66:67] neg_lo:[1,0,0] neg_hi:[1,0,0]
	s_nop 0
	v_cndmask_b32_e32 v67, v69, v73, vcc
	v_cmp_gt_f32_e32 vcc, 0, v66
	s_nop 1
	v_cndmask_b32_e32 v66, v68, v72, vcc
	v_pk_mul_f32 v[66:67], v[70:71], v[66:67]
	s_nop 0
	v_cvt_pk_bf16_f32 v65, v66, v67
	v_mad_u32_u24 v66, v124, s70, v153
	v_readlane_b32 s70, v242, 0
	global_store_dwordx2 v66, v[64:65], s[26:27]

.Lffe_807:
	s_mov_b32 s50, 0xbf3a00e3
	v_fma_f32 v60, |v48|, s74, 1.0
	v_fma_f32 v61, |v49|, s74, 1.0
	v_mov_b64_e32 v[108:109], s[50:51]
	v_rcp_f32_e32 v60, v60
	v_rcp_f32_e32 v61, v61
	s_mov_b32 s50, 0x3f07dc22
	v_mul_f32_e32 v62, v48, v48
	v_pk_fma_f32 v[110:111], v[60:61], s[50:51], v[108:109] op_sel_hi:[1,0,0]
	v_mul_f32_e32 v63, v49, v49
	v_pk_fma_f32 v[110:111], v[60:61], v[110:111], s[28:29] op_sel_hi:[1,1,0]
	v_mul_f32_e32 v62, 0xbf38aa3b, v62
	v_pk_fma_f32 v[110:111], v[60:61], v[110:111], s[76:77] op_sel_hi:[1,1,0]
	v_mul_f32_e32 v63, 0xbf38aa3b, v63
	v_pk_fma_f32 v[110:111], v[60:61], v[110:111], s[8:9] op_sel_hi:[1,1,0]
	v_exp_f32_e32 v62, v62
	v_exp_f32_e32 v63, v63
	v_pk_mul_f32 v[60:61], v[60:61], v[110:111]
	v_cmp_gt_f32_e32 vcc, 0, v49
	v_pk_mul_f32 v[60:61], v[62:63], v[60:61]
	s_nop 0
	v_pk_mul_f32 v[62:63], v[48:49], v[60:61]
	v_pk_fma_f32 v[60:61], v[48:49], v[60:61], v[48:49] neg_lo:[1,0,0] neg_hi:[1,0,0]
	s_nop 0
	v_cndmask_b32_e32 v49, v61, v63, vcc
	v_cmp_gt_f32_e32 vcc, 0, v48
	s_nop 1
	v_cndmask_b32_e32 v48, v60, v62, vcc
	v_pk_mul_f32 v[48:49], v[52:53], v[48:49]
	v_cmp_gt_f32_e32 vcc, 0, v51
	v_cvt_pk_bf16_f32 v48, v48, v49
	v_fma_f32 v49, |v50|, s74, 1.0
	v_rcp_f32_e32 v52, v49
	v_fma_f32 v49, |v51|, s74, 1.0
	v_rcp_f32_e32 v53, v49
	v_mul_f32_e32 v49, v50, v50
	v_pk_fma_f32 v[62:63], v[52:53], s[50:51], v[108:109] op_sel_hi:[1,0,0]
	v_mul_f32_e32 v49, 0xbf38aa3b, v49
	v_pk_fma_f32 v[62:63], v[52:53], v[62:63], s[28:29] op_sel_hi:[1,1,0]
	v_exp_f32_e32 v60, v49
	v_pk_fma_f32 v[62:63], v[52:53], v[62:63], s[76:77] op_sel_hi:[1,1,0]
	v_mul_f32_e32 v49, v51, v51
	v_pk_fma_f32 v[62:63], v[52:53], v[62:63], s[8:9] op_sel_hi:[1,1,0]
	v_mul_f32_e32 v49, 0xbf38aa3b, v49
	v_exp_f32_e32 v61, v49
	v_pk_mul_f32 v[52:53], v[52:53], v[62:63]
	s_movk_i32 s50, 0x1600
	v_pk_mul_f32 v[52:53], v[60:61], v[52:53]
	s_nop 0
	v_pk_mul_f32 v[60:61], v[50:51], v[52:53]
	v_pk_fma_f32 v[52:53], v[50:51], v[52:53], v[50:51] neg_lo:[1,0,0] neg_hi:[1,0,0]
	s_nop 0
	v_cndmask_b32_e32 v51, v53, v61, vcc
	v_cmp_gt_f32_e32 vcc, 0, v50
	s_nop 1
	v_cndmask_b32_e32 v50, v52, v60, vcc
	v_pk_mul_f32 v[50:51], v[54:55], v[50:51]
	s_nop 0
	v_cvt_pk_bf16_f32 v49, v50, v51
	v_mad_u32_u24 v50, v155, s50, v153
	global_store_dwordx2 v50, v[48:49], s[26:27] offset:8

.Lffe_813:
	s_mov_b32 s12, 0xbf3a00e3
	v_fma_f32 v48, |v40|, s74, 1.0
	v_fma_f32 v49, |v41|, s74, 1.0
	v_mov_b64_e32 v[52:53], s[12:13]
	v_rcp_f32_e32 v48, v48
	v_rcp_f32_e32 v49, v49
	s_mov_b32 s12, 0x3f07dc22
	v_mul_f32_e32 v50, v40, v40
	v_pk_fma_f32 v[54:55], v[48:49], s[12:13], v[52:53] op_sel_hi:[1,0,0]
	v_mul_f32_e32 v51, v41, v41
	v_pk_fma_f32 v[54:55], v[48:49], v[54:55], s[28:29] op_sel_hi:[1,1,0]
	v_mul_f32_e32 v50, 0xbf38aa3b, v50
	v_pk_fma_f32 v[54:55], v[48:49], v[54:55], s[50:51] op_sel_hi:[1,1,0]
	v_mul_f32_e32 v51, 0xbf38aa3b, v51
	v_pk_fma_f32 v[54:55], v[48:49], v[54:55], s[8:9] op_sel_hi:[1,1,0]
	v_exp_f32_e32 v50, v50
	v_exp_f32_e32 v51, v51
	v_pk_mul_f32 v[48:49], v[48:49], v[54:55]
	v_cmp_gt_f32_e32 vcc, 0, v41
	v_pk_mul_f32 v[48:49], v[50:51], v[48:49]
	s_nop 0
	v_pk_mul_f32 v[50:51], v[40:41], v[48:49]
	v_pk_fma_f32 v[48:49], v[40:41], v[48:49], v[40:41] neg_lo:[1,0,0] neg_hi:[1,0,0]
	s_nop 0
	v_cndmask_b32_e32 v41, v49, v51, vcc
	v_cmp_gt_f32_e32 vcc, 0, v40
	s_nop 1
	v_cndmask_b32_e32 v40, v48, v50, vcc
	v_pk_mul_f32 v[40:41], v[44:45], v[40:41]
	v_cmp_gt_f32_e32 vcc, 0, v43
	v_cvt_pk_bf16_f32 v40, v40, v41
	v_fma_f32 v41, |v42|, s74, 1.0
	v_rcp_f32_e32 v44, v41
	v_fma_f32 v41, |v43|, s74, 1.0
	v_rcp_f32_e32 v45, v41
	v_mul_f32_e32 v41, v42, v42
	v_pk_fma_f32 v[50:51], v[44:45], s[12:13], v[52:53] op_sel_hi:[1,0,0]
	v_mul_f32_e32 v41, 0xbf38aa3b, v41
	v_pk_fma_f32 v[50:51], v[44:45], v[50:51], s[28:29] op_sel_hi:[1,1,0]
	v_exp_f32_e32 v48, v41
	v_pk_fma_f32 v[50:51], v[44:45], v[50:51], s[50:51] op_sel_hi:[1,1,0]
	v_mul_f32_e32 v41, v43, v43
	v_pk_fma_f32 v[50:51], v[44:45], v[50:51], s[8:9] op_sel_hi:[1,1,0]
	v_mul_f32_e32 v41, 0xbf38aa3b, v41
	v_exp_f32_e32 v49, v41
	v_pk_mul_f32 v[44:45], v[44:45], v[50:51]
	s_movk_i32 s12, 0x1600
	v_pk_mul_f32 v[44:45], v[48:49], v[44:45]
	s_nop 0
	v_pk_mul_f32 v[48:49], v[42:43], v[44:45]
	v_pk_fma_f32 v[44:45], v[42:43], v[44:45], v[42:43] neg_lo:[1,0,0] neg_hi:[1,0,0]
	s_nop 0
	v_cndmask_b32_e32 v43, v45, v49, vcc
	v_cmp_gt_f32_e32 vcc, 0, v42
	s_nop 1
	v_cndmask_b32_e32 v42, v44, v48, vcc
	v_pk_mul_f32 v[42:43], v[46:47], v[42:43]
	s_nop 0
	v_cvt_pk_bf16_f32 v41, v42, v43
	v_mad_u32_u24 v42, v145, s12, v153
	global_store_dwordx2 v42, v[40:41], s[26:27] offset:8

.Lffe_819:
	s_mov_b32 s14, 0xbf3a00e3
	v_fma_f32 v40, |v32|, s74, 1.0
	v_fma_f32 v41, |v33|, s74, 1.0
	v_mov_b64_e32 v[44:45], s[14:15]
	v_rcp_f32_e32 v40, v40
	v_rcp_f32_e32 v41, v41
	s_mov_b32 s14, 0x3f07dc22
	v_mul_f32_e32 v42, v32, v32
	v_pk_fma_f32 v[46:47], v[40:41], s[14:15], v[44:45] op_sel_hi:[1,0,0]
	v_mul_f32_e32 v43, v33, v33
	v_pk_fma_f32 v[46:47], v[40:41], v[46:47], s[28:29] op_sel_hi:[1,1,0]
	v_mul_f32_e32 v42, 0xbf38aa3b, v42
	v_pk_fma_f32 v[46:47], v[40:41], v[46:47], s[48:49] op_sel_hi:[1,1,0]
	v_mul_f32_e32 v43, 0xbf38aa3b, v43
	v_pk_fma_f32 v[46:47], v[40:41], v[46:47], s[8:9] op_sel_hi:[1,1,0]
	v_exp_f32_e32 v42, v42
	v_exp_f32_e32 v43, v43
	v_pk_mul_f32 v[40:41], v[40:41], v[46:47]
	v_cmp_gt_f32_e32 vcc, 0, v33
	v_pk_mul_f32 v[40:41], v[42:43], v[40:41]
	s_nop 0
	v_pk_mul_f32 v[42:43], v[32:33], v[40:41]
	v_pk_fma_f32 v[40:41], v[32:33], v[40:41], v[32:33] neg_lo:[1,0,0] neg_hi:[1,0,0]
	s_nop 0
	v_cndmask_b32_e32 v33, v41, v43, vcc
	v_cmp_gt_f32_e32 vcc, 0, v32
	s_nop 1
	v_cndmask_b32_e32 v32, v40, v42, vcc
	v_pk_mul_f32 v[32:33], v[36:37], v[32:33]
	v_cmp_gt_f32_e32 vcc, 0, v35
	v_cvt_pk_bf16_f32 v32, v32, v33
	v_fma_f32 v33, |v34|, s74, 1.0
	v_rcp_f32_e32 v36, v33
	v_fma_f32 v33, |v35|, s74, 1.0
	v_rcp_f32_e32 v37, v33
	v_mul_f32_e32 v33, v34, v34
	v_pk_fma_f32 v[42:43], v[36:37], s[14:15], v[44:45] op_sel_hi:[1,0,0]
	v_mul_f32_e32 v33, 0xbf38aa3b, v33
	v_pk_fma_f32 v[42:43], v[36:37], v[42:43], s[28:29] op_sel_hi:[1,1,0]
	v_exp_f32_e32 v40, v33
	v_pk_fma_f32 v[42:43], v[36:37], v[42:43], s[48:49] op_sel_hi:[1,1,0]
	v_mul_f32_e32 v33, v35, v35
	v_pk_fma_f32 v[42:43], v[36:37], v[42:43], s[8:9] op_sel_hi:[1,1,0]
	v_mul_f32_e32 v33, 0xbf38aa3b, v33
	v_exp_f32_e32 v41, v33
	v_pk_mul_f32 v[36:37], v[36:37], v[42:43]
	s_movk_i32 s14, 0x1600
	v_pk_mul_f32 v[36:37], v[40:41], v[36:37]
	s_nop 0
	v_pk_mul_f32 v[40:41], v[34:35], v[36:37]
	v_pk_fma_f32 v[36:37], v[34:35], v[36:37], v[34:35] neg_lo:[1,0,0] neg_hi:[1,0,0]
	s_nop 0
	v_cndmask_b32_e32 v35, v37, v41, vcc
	v_cmp_gt_f32_e32 vcc, 0, v34
	s_nop 1
	v_cndmask_b32_e32 v34, v36, v40, vcc
	v_pk_mul_f32 v[34:35], v[38:39], v[34:35]
	s_nop 0
	v_cvt_pk_bf16_f32 v33, v34, v35
	v_mad_u32_u24 v34, v210, s14, v153
	global_store_dwordx2 v34, v[32:33], s[26:27] offset:8

.Lffe_825:
	s_mov_b32 s14, 0xbf3a00e3
	v_fma_f32 v40, |v32|, s74, 1.0
	v_fma_f32 v41, |v33|, s74, 1.0
	v_mov_b64_e32 v[44:45], s[14:15]
	v_rcp_f32_e32 v40, v40
	v_rcp_f32_e32 v41, v41
	s_mov_b32 s14, 0x3f07dc22
	v_mul_f32_e32 v42, v32, v32
	v_pk_fma_f32 v[46:47], v[40:41], s[14:15], v[44:45] op_sel_hi:[1,0,0]
	v_mul_f32_e32 v43, v33, v33
	v_pk_fma_f32 v[46:47], v[40:41], v[46:47], s[28:29] op_sel_hi:[1,1,0]
	v_mul_f32_e32 v42, 0xbf38aa3b, v42
	v_pk_fma_f32 v[46:47], v[40:41], v[46:47], s[48:49] op_sel_hi:[1,1,0]
	v_mul_f32_e32 v43, 0xbf38aa3b, v43
	v_pk_fma_f32 v[46:47], v[40:41], v[46:47], s[8:9] op_sel_hi:[1,1,0]
	v_exp_f32_e32 v42, v42
	v_exp_f32_e32 v43, v43
	v_pk_mul_f32 v[40:41], v[40:41], v[46:47]
	v_cmp_gt_f32_e32 vcc, 0, v33
	v_pk_mul_f32 v[40:41], v[42:43], v[40:41]
	s_nop 0
	v_pk_mul_f32 v[42:43], v[32:33], v[40:41]
	v_pk_fma_f32 v[40:41], v[32:33], v[40:41], v[32:33] neg_lo:[1,0,0] neg_hi:[1,0,0]
	s_nop 0
	v_cndmask_b32_e32 v33, v41, v43, vcc
	v_cmp_gt_f32_e32 vcc, 0, v32
	s_nop 1
	v_cndmask_b32_e32 v32, v40, v42, vcc
	v_pk_mul_f32 v[32:33], v[36:37], v[32:33]
	v_cmp_gt_f32_e32 vcc, 0, v35
	v_cvt_pk_bf16_f32 v32, v32, v33
	v_fma_f32 v33, |v34|, s74, 1.0
	v_rcp_f32_e32 v36, v33
	v_fma_f32 v33, |v35|, s74, 1.0
	v_rcp_f32_e32 v37, v33
	v_mul_f32_e32 v33, v34, v34
	v_pk_fma_f32 v[42:43], v[36:37], s[14:15], v[44:45] op_sel_hi:[1,0,0]
	v_mul_f32_e32 v33, 0xbf38aa3b, v33
	v_pk_fma_f32 v[42:43], v[36:37], v[42:43], s[28:29] op_sel_hi:[1,1,0]
	v_exp_f32_e32 v40, v33
	v_pk_fma_f32 v[42:43], v[36:37], v[42:43], s[48:49] op_sel_hi:[1,1,0]
	v_mul_f32_e32 v33, v35, v35
	v_pk_fma_f32 v[42:43], v[36:37], v[42:43], s[8:9] op_sel_hi:[1,1,0]
	v_mul_f32_e32 v33, 0xbf38aa3b, v33
	v_exp_f32_e32 v41, v33
	v_pk_mul_f32 v[36:37], v[36:37], v[42:43]
	s_movk_i32 s14, 0x1600
	v_pk_mul_f32 v[36:37], v[40:41], v[36:37]
	s_nop 0
	v_pk_mul_f32 v[40:41], v[34:35], v[36:37]
	v_pk_fma_f32 v[36:37], v[34:35], v[36:37], v[34:35] neg_lo:[1,0,0] neg_hi:[1,0,0]
	s_nop 0
	v_cndmask_b32_e32 v35, v37, v41, vcc
	v_cmp_gt_f32_e32 vcc, 0, v34
	s_nop 1
	v_cndmask_b32_e32 v34, v36, v40, vcc
	v_pk_mul_f32 v[34:35], v[38:39], v[34:35]
	s_nop 0
	v_cvt_pk_bf16_f32 v33, v34, v35
	v_mad_u32_u24 v34, v200, s14, v153
	global_store_dwordx2 v34, v[32:33], s[26:27] offset:8

.Lffe_828:
	s_mov_b32 s14, 0xbf3a00e3
	v_fma_f32 v24, |v16|, s74, 1.0
	v_fma_f32 v25, |v17|, s74, 1.0
	v_mov_b64_e32 v[28:29], s[14:15]
	v_rcp_f32_e32 v24, v24
	v_rcp_f32_e32 v25, v25
	s_mov_b32 s14, 0x3f07dc22
	v_mul_f32_e32 v26, v16, v16
	v_pk_fma_f32 v[30:31], v[24:25], s[14:15], v[28:29] op_sel_hi:[1,0,0]
	v_mul_f32_e32 v27, v17, v17
	v_pk_fma_f32 v[30:31], v[24:25], v[30:31], s[28:29] op_sel_hi:[1,1,0]
	v_mul_f32_e32 v26, 0xbf38aa3b, v26
	v_pk_fma_f32 v[30:31], v[24:25], v[30:31], s[48:49] op_sel_hi:[1,1,0]
	v_mul_f32_e32 v27, 0xbf38aa3b, v27
	v_pk_fma_f32 v[30:31], v[24:25], v[30:31], s[8:9] op_sel_hi:[1,1,0]
	v_exp_f32_e32 v26, v26
	v_exp_f32_e32 v27, v27
	v_pk_mul_f32 v[24:25], v[24:25], v[30:31]
	v_cmp_gt_f32_e32 vcc, 0, v17
	v_pk_mul_f32 v[24:25], v[26:27], v[24:25]
	s_nop 0
	v_pk_mul_f32 v[26:27], v[16:17], v[24:25]
	v_pk_fma_f32 v[24:25], v[16:17], v[24:25], v[16:17] neg_lo:[1,0,0] neg_hi:[1,0,0]
	s_nop 0
	v_cndmask_b32_e32 v17, v25, v27, vcc
	v_cmp_gt_f32_e32 vcc, 0, v16
	s_nop 1
	v_cndmask_b32_e32 v16, v24, v26, vcc
	v_pk_mul_f32 v[16:17], v[20:21], v[16:17]
	v_cmp_gt_f32_e32 vcc, 0, v19
	v_cvt_pk_bf16_f32 v16, v16, v17
	v_fma_f32 v17, |v18|, s74, 1.0
	v_rcp_f32_e32 v20, v17
	v_fma_f32 v17, |v19|, s74, 1.0
	v_rcp_f32_e32 v21, v17
	v_mul_f32_e32 v17, v18, v18
	v_pk_fma_f32 v[26:27], v[20:21], s[14:15], v[28:29] op_sel_hi:[1,0,0]
	v_mul_f32_e32 v17, 0xbf38aa3b, v17
	v_pk_fma_f32 v[26:27], v[20:21], v[26:27], s[28:29] op_sel_hi:[1,1,0]
	v_exp_f32_e32 v24, v17
	v_pk_fma_f32 v[26:27], v[20:21], v[26:27], s[48:49] op_sel_hi:[1,1,0]
	v_mul_f32_e32 v17, v19, v19
	v_pk_fma_f32 v[26:27], v[20:21], v[26:27], s[8:9] op_sel_hi:[1,1,0]
	v_mul_f32_e32 v17, 0xbf38aa3b, v17
	v_exp_f32_e32 v25, v17
	v_pk_mul_f32 v[20:21], v[20:21], v[26:27]
	s_movk_i32 s14, 0x1600
	v_pk_mul_f32 v[20:21], v[24:25], v[20:21]
	s_nop 0
	v_pk_mul_f32 v[24:25], v[18:19], v[20:21]
	v_pk_fma_f32 v[20:21], v[18:19], v[20:21], v[18:19] neg_lo:[1,0,0] neg_hi:[1,0,0]
	s_nop 0
	v_cndmask_b32_e32 v19, v21, v25, vcc
	v_cmp_gt_f32_e32 vcc, 0, v18
	s_nop 1
	v_cndmask_b32_e32 v18, v20, v24, vcc
	v_pk_mul_f32 v[18:19], v[22:23], v[18:19]
	s_nop 0
	v_cvt_pk_bf16_f32 v17, v18, v19
	v_mad_u32_u24 v18, v105, s14, v153
	global_store_dwordx2 v18, v[16:17], s[26:27] offset:8

.Lffe_834:
	s_mov_b32 s14, 0xbf3a00e3
	v_fma_f32 v16, |v8|, s74, 1.0
	v_fma_f32 v17, |v9|, s74, 1.0
	v_mov_b64_e32 v[20:21], s[14:15]
	v_rcp_f32_e32 v16, v16
	v_rcp_f32_e32 v17, v17
	s_mov_b32 s14, 0x3f07dc22
	v_mul_f32_e32 v18, v8, v8
	v_pk_fma_f32 v[22:23], v[16:17], s[14:15], v[20:21] op_sel_hi:[1,0,0]
	v_mul_f32_e32 v19, v9, v9
	v_pk_fma_f32 v[22:23], v[16:17], v[22:23], s[16:17] op_sel_hi:[1,1,0]
	v_mul_f32_e32 v18, 0xbf38aa3b, v18
	v_pk_fma_f32 v[22:23], v[16:17], v[22:23], s[28:29] op_sel_hi:[1,1,0]
	v_mul_f32_e32 v19, 0xbf38aa3b, v19
	v_pk_fma_f32 v[22:23], v[16:17], v[22:23], s[8:9] op_sel_hi:[1,1,0]
	v_exp_f32_e32 v18, v18
	v_exp_f32_e32 v19, v19
	v_pk_mul_f32 v[16:17], v[16:17], v[22:23]
	v_cmp_gt_f32_e32 vcc, 0, v9
	v_pk_mul_f32 v[16:17], v[18:19], v[16:17]
	s_nop 0
	v_pk_mul_f32 v[18:19], v[8:9], v[16:17]
	v_pk_fma_f32 v[16:17], v[8:9], v[16:17], v[8:9] neg_lo:[1,0,0] neg_hi:[1,0,0]
	s_nop 0
	v_cndmask_b32_e32 v9, v17, v19, vcc
	v_cmp_gt_f32_e32 vcc, 0, v8
	s_nop 1
	v_cndmask_b32_e32 v8, v16, v18, vcc
	v_pk_mul_f32 v[8:9], v[12:13], v[8:9]
	v_cmp_gt_f32_e32 vcc, 0, v11
	v_cvt_pk_bf16_f32 v8, v8, v9
	v_fma_f32 v9, |v10|, s74, 1.0
	v_rcp_f32_e32 v12, v9
	v_fma_f32 v9, |v11|, s74, 1.0
	v_rcp_f32_e32 v13, v9
	v_mul_f32_e32 v9, v10, v10
	v_pk_fma_f32 v[18:19], v[12:13], s[14:15], v[20:21] op_sel_hi:[1,0,0]
	v_mul_f32_e32 v9, 0xbf38aa3b, v9
	v_pk_fma_f32 v[18:19], v[12:13], v[18:19], s[16:17] op_sel_hi:[1,1,0]
	v_exp_f32_e32 v16, v9
	v_pk_fma_f32 v[18:19], v[12:13], v[18:19], s[28:29] op_sel_hi:[1,1,0]
	v_mul_f32_e32 v9, v11, v11
	v_pk_fma_f32 v[18:19], v[12:13], v[18:19], s[8:9] op_sel_hi:[1,1,0]
	v_mul_f32_e32 v9, 0xbf38aa3b, v9
	v_exp_f32_e32 v17, v9
	v_pk_mul_f32 v[12:13], v[12:13], v[18:19]
	s_movk_i32 s14, 0x1600
	v_pk_mul_f32 v[12:13], v[16:17], v[12:13]
	s_nop 0
	v_pk_mul_f32 v[16:17], v[10:11], v[12:13]
	v_pk_fma_f32 v[12:13], v[10:11], v[12:13], v[10:11] neg_lo:[1,0,0] neg_hi:[1,0,0]
	s_nop 0
	v_cndmask_b32_e32 v11, v13, v17, vcc
	v_cmp_gt_f32_e32 vcc, 0, v10
	s_nop 1
	v_cndmask_b32_e32 v10, v12, v16, vcc
	v_pk_mul_f32 v[10:11], v[14:15], v[10:11]
	s_nop 0
	v_cvt_pk_bf16_f32 v9, v10, v11
	v_mad_u32_u24 v10, v97, s14, v153
	global_store_dwordx2 v10, v[8:9], s[26:27] offset:8

.Lffe_840:
	s_mov_b32 s14, 0xbf3a00e3
	v_fma_f32 v8, |v0|, s74, 1.0
	v_fma_f32 v9, |v1|, s74, 1.0
	v_mov_b64_e32 v[12:13], s[14:15]
	v_rcp_f32_e32 v8, v8
	v_rcp_f32_e32 v9, v9
	s_mov_b32 s14, 0x3f07dc22
	v_mul_f32_e32 v10, v0, v0
	v_pk_fma_f32 v[14:15], v[8:9], s[14:15], v[12:13] op_sel_hi:[1,0,0]
	v_mul_f32_e32 v11, v1, v1
	v_pk_fma_f32 v[14:15], v[8:9], v[14:15], s[16:17] op_sel_hi:[1,1,0]
	v_mul_f32_e32 v10, 0xbf38aa3b, v10
	v_pk_fma_f32 v[14:15], v[8:9], v[14:15], s[18:19] op_sel_hi:[1,1,0]
	v_mul_f32_e32 v11, 0xbf38aa3b, v11
	v_pk_fma_f32 v[14:15], v[8:9], v[14:15], s[8:9] op_sel_hi:[1,1,0]
	v_exp_f32_e32 v10, v10
	v_exp_f32_e32 v11, v11
	v_pk_mul_f32 v[8:9], v[8:9], v[14:15]
	v_cmp_gt_f32_e32 vcc, 0, v1
	v_pk_mul_f32 v[8:9], v[10:11], v[8:9]
	s_nop 0
	v_pk_mul_f32 v[10:11], v[0:1], v[8:9]
	v_pk_fma_f32 v[8:9], v[0:1], v[8:9], v[0:1] neg_lo:[1,0,0] neg_hi:[1,0,0]
	s_nop 0
	v_cndmask_b32_e32 v1, v9, v11, vcc
	v_cmp_gt_f32_e32 vcc, 0, v0
	s_nop 1
	v_cndmask_b32_e32 v0, v8, v10, vcc
	v_pk_mul_f32 v[0:1], v[4:5], v[0:1]
	v_cmp_gt_f32_e32 vcc, 0, v3
	v_cvt_pk_bf16_f32 v0, v0, v1
	v_fma_f32 v1, |v2|, s74, 1.0
	v_rcp_f32_e32 v4, v1
	v_fma_f32 v1, |v3|, s74, 1.0
	v_rcp_f32_e32 v5, v1
	v_mul_f32_e32 v1, v2, v2
	v_pk_fma_f32 v[10:11], v[4:5], s[14:15], v[12:13] op_sel_hi:[1,0,0]
	v_mul_f32_e32 v1, 0xbf38aa3b, v1
	v_pk_fma_f32 v[10:11], v[4:5], v[10:11], s[16:17] op_sel_hi:[1,1,0]
	v_exp_f32_e32 v8, v1
	v_pk_fma_f32 v[10:11], v[4:5], v[10:11], s[18:19] op_sel_hi:[1,1,0]
	v_mul_f32_e32 v1, v3, v3
	v_pk_fma_f32 v[10:11], v[4:5], v[10:11], s[8:9] op_sel_hi:[1,1,0]
	v_mul_f32_e32 v1, 0xbf38aa3b, v1
	v_exp_f32_e32 v9, v1
	v_pk_mul_f32 v[4:5], v[4:5], v[10:11]
	s_movk_i32 s14, 0x1600
	v_pk_mul_f32 v[4:5], v[8:9], v[4:5]
	s_nop 0
	v_pk_mul_f32 v[8:9], v[2:3], v[4:5]
	v_pk_fma_f32 v[4:5], v[2:3], v[4:5], v[2:3] neg_lo:[1,0,0] neg_hi:[1,0,0]
	s_nop 0
	v_cndmask_b32_e32 v3, v5, v9, vcc
	v_cmp_gt_f32_e32 vcc, 0, v2
	s_nop 1
	v_cndmask_b32_e32 v2, v4, v8, vcc
	v_pk_mul_f32 v[2:3], v[6:7], v[2:3]
	s_nop 0
	v_cvt_pk_bf16_f32 v1, v2, v3
	v_mad_u32_u24 v2, v146, s14, v153
	global_store_dwordx2 v2, v[0:1], s[26:27] offset:8

.Lffe_846:
	s_mov_b32 s14, 0xbf3a00e3
	v_fma_f32 v8, |v0|, s74, 1.0
	v_fma_f32 v9, |v1|, s74, 1.0
	v_mov_b64_e32 v[12:13], s[14:15]
	v_rcp_f32_e32 v8, v8
	v_rcp_f32_e32 v9, v9
	s_mov_b32 s14, 0x3f07dc22
	v_mul_f32_e32 v10, v0, v0
	v_pk_fma_f32 v[14:15], v[8:9], s[14:15], v[12:13] op_sel_hi:[1,0,0]
	v_mul_f32_e32 v11, v1, v1
	v_pk_fma_f32 v[14:15], v[8:9], v[14:15], s[16:17] op_sel_hi:[1,1,0]
	v_mul_f32_e32 v10, 0xbf38aa3b, v10
	v_pk_fma_f32 v[14:15], v[8:9], v[14:15], s[18:19] op_sel_hi:[1,1,0]
	v_mul_f32_e32 v11, 0xbf38aa3b, v11
	v_pk_fma_f32 v[14:15], v[8:9], v[14:15], s[8:9] op_sel_hi:[1,1,0]
	v_exp_f32_e32 v10, v10
	v_exp_f32_e32 v11, v11
	v_pk_mul_f32 v[8:9], v[8:9], v[14:15]
	v_cmp_gt_f32_e32 vcc, 0, v1
	v_pk_mul_f32 v[8:9], v[10:11], v[8:9]
	s_nop 0
	v_pk_mul_f32 v[10:11], v[0:1], v[8:9]
	v_pk_fma_f32 v[8:9], v[0:1], v[8:9], v[0:1] neg_lo:[1,0,0] neg_hi:[1,0,0]
	s_nop 0
	v_cndmask_b32_e32 v1, v9, v11, vcc
	v_cmp_gt_f32_e32 vcc, 0, v0
	s_nop 1
	v_cndmask_b32_e32 v0, v8, v10, vcc
	v_pk_mul_f32 v[0:1], v[4:5], v[0:1]
	v_cmp_gt_f32_e32 vcc, 0, v3
	v_cvt_pk_bf16_f32 v0, v0, v1
	v_fma_f32 v1, |v2|, s74, 1.0
	v_rcp_f32_e32 v4, v1
	v_fma_f32 v1, |v3|, s74, 1.0
	v_rcp_f32_e32 v5, v1
	v_mul_f32_e32 v1, v2, v2
	v_pk_fma_f32 v[10:11], v[4:5], s[14:15], v[12:13] op_sel_hi:[1,0,0]
	v_mul_f32_e32 v1, 0xbf38aa3b, v1
	v_pk_fma_f32 v[10:11], v[4:5], v[10:11], s[16:17] op_sel_hi:[1,1,0]
	v_exp_f32_e32 v8, v1
	v_pk_fma_f32 v[10:11], v[4:5], v[10:11], s[18:19] op_sel_hi:[1,1,0]
	v_mul_f32_e32 v1, v3, v3
	v_pk_fma_f32 v[10:11], v[4:5], v[10:11], s[8:9] op_sel_hi:[1,1,0]
	v_mul_f32_e32 v1, 0xbf38aa3b, v1
	v_exp_f32_e32 v9, v1
	v_pk_mul_f32 v[4:5], v[4:5], v[10:11]
	s_movk_i32 s14, 0x1600
	v_pk_mul_f32 v[4:5], v[8:9], v[4:5]
	s_nop 0
	v_pk_mul_f32 v[8:9], v[2:3], v[4:5]
	v_pk_fma_f32 v[4:5], v[2:3], v[4:5], v[2:3] neg_lo:[1,0,0] neg_hi:[1,0,0]
	s_nop 0
	v_cndmask_b32_e32 v3, v5, v9, vcc
	v_cmp_gt_f32_e32 vcc, 0, v2
	s_nop 1
	v_cndmask_b32_e32 v2, v4, v8, vcc
	v_pk_mul_f32 v[2:3], v[6:7], v[2:3]
	s_nop 0
	v_cvt_pk_bf16_f32 v1, v2, v3
	v_mad_u32_u24 v2, v124, s14, v153
	global_store_dwordx2 v2, v[0:1], s[26:27] offset:8
	s_or_b64 exec, exec, s[12:13]
	s_andn2_b64 vcc, exec, s[46:47]
	s_mov_b64 s[12:13], -1
	s_cbranch_vccnz .LBB0_736

.LBB0_930:
	v_lshl_add_u32 v140, s49, 8, v144
	v_lshl_or_b32 v138, s50, 8, v146
	v_ashrrev_i32_e32 v141, 31, v140
	v_ashrrev_i32_e32 v139, 31, v138
	v_lshlrev_b64 v[142:143], 11, v[140:141]
	v_lshl_add_u64 v[148:149], s[10:11], 0, v[142:143]
	v_lshlrev_b64 v[142:143], 1, v[138:139]
	v_lshl_add_u64 v[152:153], v[148:149], 0, v[142:143]
	v_subrev_u32_e32 v240, s10, v152
	global_load_dwordx4 v[184:187], v240, s[10:11]
	global_load_dwordx4 v[188:191], v240, s[10:11] offset:256
	v_add_u32_e32 v241, 0x8000, v240
	global_load_dwordx4 v[192:195], v241, s[10:11]
	v_add_u32_e32 v241, 0x8000, v240
	global_load_dwordx4 v[196:199], v241, s[10:11] offset:256
	v_add_u32_e32 v241, 0x10000, v240
	global_load_dwordx4 v[200:203], v241, s[10:11]
	v_add_u32_e32 v241, 0x10000, v240
	global_load_dwordx4 v[204:207], v241, s[10:11] offset:256
	v_add_u32_e32 v241, 0x18000, v240
	global_load_dwordx4 v[208:211], v241, s[10:11]
	v_add_u32_e32 v241, 0x18000, v240
	global_load_dwordx4 v[212:215], v241, s[10:11] offset:256
	v_add_u32_e32 v241, 0x40000, v240
	global_load_dwordx4 v[220:223], v241, s[10:11]
	v_add_u32_e32 v241, 0x40000, v240
	global_load_dwordx4 v[224:227], v241, s[10:11] offset:256
	v_add_u32_e32 v241, 0x48000, v240
	global_load_dwordx4 v[228:231], v241, s[10:11]
	v_add_u32_e32 v241, 0x48000, v240
	global_load_dwordx4 v[232:235], v241, s[10:11] offset:256
	s_waitcnt vmcnt(11)
	s_nop 1
	v_mov_b64_e32 v[148:149], v[184:185]
	v_mov_b64_e32 v[150:151], v[186:187]
	v_add_u32_e32 v241, 0x50000, v240
	global_load_dwordx4 v[184:187], v241, s[10:11]
	v_lshlrev_b64 v[154:155], 12, v[140:141]
	v_lshlrev_b64 v[138:139], 2, v[138:139]
	v_lshl_add_u64 v[154:155], s[12:13], 0, v[154:155]
	v_lshl_add_u64 v[154:155], v[154:155], 0, v[138:139]
	s_and_b64 vcc, exec, s[4:5]
	s_mov_b64 s[4:5], -1
	v_lshlrev_b32_e32 v156, 16, v148
	v_and_b32_e32 v157, 0xffff0000, v148
	v_lshlrev_b32_e32 v148, 16, v149
	v_and_b32_e32 v149, 0xffff0000, v149
	v_lshlrev_b32_e32 v158, 16, v150
	v_and_b32_e32 v159, 0xffff0000, v150
	v_lshlrev_b32_e32 v150, 16, v151
	v_and_b32_e32 v151, 0xffff0000, v151
	v_pk_add_f32 v[124:125], v[124:125], v[156:157]
	v_pk_add_f32 v[126:127], v[126:127], v[148:149]
	v_pk_add_f32 v[120:121], v[120:121], v[158:159]
	v_pk_add_f32 v[122:123], v[122:123], v[150:151]
	global_store_dwordx4 v[154:155], v[124:127], off
	global_store_dwordx4 v[154:155], v[120:123], off offset:16
	s_waitcnt vmcnt(11)
	s_nop 1
	v_mov_b64_e32 v[120:121], v[188:189]
	v_mov_b64_e32 v[122:123], v[190:191]
	v_add_u32_e32 v241, 0x50000, v240
	global_load_dwordx4 v[188:191], v241, s[10:11] offset:256
	v_or_b32_e32 v124, 16, v140
	v_ashrrev_i32_e32 v125, 31, v124
	v_lshlrev_b64 v[126:127], 11, v[124:125]
	v_lshl_add_u64 v[126:127], s[10:11], 0, v[126:127]
	v_lshl_add_u64 v[126:127], v[126:127], 0, v[142:143]
	v_lshlrev_b32_e32 v148, 16, v120
	v_and_b32_e32 v149, 0xffff0000, v120
	v_lshlrev_b32_e32 v120, 16, v121
	v_and_b32_e32 v121, 0xffff0000, v121
	v_lshlrev_b32_e32 v150, 16, v122
	v_and_b32_e32 v151, 0xffff0000, v122
	v_lshlrev_b32_e32 v122, 16, v123
	v_and_b32_e32 v123, 0xffff0000, v123
	v_pk_add_f32 v[116:117], v[116:117], v[148:149]
	v_pk_add_f32 v[118:119], v[118:119], v[120:121]
	v_pk_add_f32 v[112:113], v[112:113], v[150:151]
	v_pk_add_f32 v[114:115], v[114:115], v[122:123]
	global_store_dwordx4 v[154:155], v[116:119], off offset:512
	global_store_dwordx4 v[154:155], v[112:115], off offset:528
	s_waitcnt vmcnt(11)
	s_nop 1
	v_mov_b64_e32 v[112:113], v[192:193]
	v_mov_b64_e32 v[114:115], v[194:195]
	v_add_u32_e32 v241, 0x58000, v240
	global_load_dwordx4 v[192:195], v241, s[10:11]
	v_lshlrev_b64 v[116:117], 12, v[124:125]
	v_lshl_add_u64 v[116:117], s[12:13], 0, v[116:117]
	v_lshl_add_u64 v[116:117], v[116:117], 0, v[138:139]
	v_lshlrev_b32_e32 v118, 16, v112
	v_and_b32_e32 v119, 0xffff0000, v112
	v_lshlrev_b32_e32 v112, 16, v113
	v_and_b32_e32 v113, 0xffff0000, v113
	v_lshlrev_b32_e32 v120, 16, v114
	v_and_b32_e32 v121, 0xffff0000, v114
	v_lshlrev_b32_e32 v114, 16, v115
	v_and_b32_e32 v115, 0xffff0000, v115
	v_pk_add_f32 v[108:109], v[108:109], v[118:119]
	v_pk_add_f32 v[110:111], v[110:111], v[112:113]
	v_pk_add_f32 v[104:105], v[104:105], v[120:121]
	v_pk_add_f32 v[106:107], v[106:107], v[114:115]
	global_store_dwordx4 v[116:117], v[108:111], off
	global_store_dwordx4 v[116:117], v[104:107], off offset:16
	s_waitcnt vmcnt(11)
	s_nop 1
	v_mov_b64_e32 v[104:105], v[196:197]
	v_mov_b64_e32 v[106:107], v[198:199]
	v_add_u32_e32 v241, 0x58000, v240
	global_load_dwordx4 v[196:199], v241, s[10:11] offset:256
	v_or_b32_e32 v108, 32, v140
	v_ashrrev_i32_e32 v109, 31, v108
	v_lshlrev_b64 v[110:111], 11, v[108:109]
	v_lshl_add_u64 v[110:111], s[10:11], 0, v[110:111]
	v_lshl_add_u64 v[110:111], v[110:111], 0, v[142:143]
	v_lshlrev_b32_e32 v112, 16, v104
	v_and_b32_e32 v113, 0xffff0000, v104
	v_lshlrev_b32_e32 v104, 16, v105
	v_and_b32_e32 v105, 0xffff0000, v105
	v_lshlrev_b32_e32 v114, 16, v106
	v_and_b32_e32 v115, 0xffff0000, v106
	v_lshlrev_b32_e32 v106, 16, v107
	v_and_b32_e32 v107, 0xffff0000, v107
	v_pk_add_f32 v[100:101], v[100:101], v[112:113]
	v_pk_add_f32 v[102:103], v[102:103], v[104:105]
	v_pk_add_f32 v[96:97], v[96:97], v[114:115]
	v_pk_add_f32 v[98:99], v[98:99], v[106:107]
	global_store_dwordx4 v[116:117], v[100:103], off offset:512
	global_store_dwordx4 v[116:117], v[96:99], off offset:528
	s_waitcnt vmcnt(11)
	s_nop 1
	v_mov_b64_e32 v[96:97], v[200:201]
	v_mov_b64_e32 v[98:99], v[202:203]
	v_lshlrev_b64 v[100:101], 12, v[108:109]
	v_lshl_add_u64 v[100:101], s[12:13], 0, v[100:101]
	v_lshl_add_u64 v[100:101], v[100:101], 0, v[138:139]
	v_lshlrev_b32_e32 v102, 16, v96
	v_and_b32_e32 v103, 0xffff0000, v96
	v_lshlrev_b32_e32 v96, 16, v97
	v_and_b32_e32 v97, 0xffff0000, v97
	v_lshlrev_b32_e32 v104, 16, v98
	v_and_b32_e32 v105, 0xffff0000, v98
	v_lshlrev_b32_e32 v98, 16, v99
	v_and_b32_e32 v99, 0xffff0000, v99
	v_pk_add_f32 v[92:93], v[92:93], v[102:103]
	v_pk_add_f32 v[94:95], v[94:95], v[96:97]
	v_pk_add_f32 v[88:89], v[88:89], v[104:105]
	v_pk_add_f32 v[90:91], v[90:91], v[98:99]
	global_store_dwordx4 v[100:101], v[92:95], off
	global_store_dwordx4 v[100:101], v[88:91], off offset:16
	s_waitcnt vmcnt(10)
	s_nop 1
	v_mov_b64_e32 v[88:89], v[204:205]
	v_mov_b64_e32 v[90:91], v[206:207]
	v_or_b32_e32 v92, 48, v140
	v_ashrrev_i32_e32 v93, 31, v92
	v_lshlrev_b64 v[94:95], 11, v[92:93]
	v_lshl_add_u64 v[94:95], s[10:11], 0, v[94:95]
	v_lshl_add_u64 v[94:95], v[94:95], 0, v[142:143]
	v_lshlrev_b32_e32 v96, 16, v88
	v_and_b32_e32 v97, 0xffff0000, v88
	v_lshlrev_b32_e32 v88, 16, v89
	v_and_b32_e32 v89, 0xffff0000, v89
	v_lshlrev_b32_e32 v98, 16, v90
	v_and_b32_e32 v99, 0xffff0000, v90
	v_lshlrev_b32_e32 v90, 16, v91
	v_and_b32_e32 v91, 0xffff0000, v91
	v_pk_add_f32 v[84:85], v[84:85], v[96:97]
	v_pk_add_f32 v[86:87], v[86:87], v[88:89]
	v_pk_add_f32 v[80:81], v[80:81], v[98:99]
	v_pk_add_f32 v[82:83], v[82:83], v[90:91]
	global_store_dwordx4 v[100:101], v[84:87], off offset:512
	global_store_dwordx4 v[100:101], v[80:83], off offset:528
	s_waitcnt vmcnt(9)
	s_nop 1
	v_mov_b64_e32 v[80:81], v[208:209]
	v_mov_b64_e32 v[82:83], v[210:211]
	v_lshlrev_b64 v[84:85], 12, v[92:93]
	v_lshl_add_u64 v[84:85], s[12:13], 0, v[84:85]
	v_lshl_add_u64 v[84:85], v[84:85], 0, v[138:139]
	v_lshlrev_b32_e32 v86, 16, v80
	v_and_b32_e32 v87, 0xffff0000, v80
	v_lshlrev_b32_e32 v80, 16, v81
	v_and_b32_e32 v81, 0xffff0000, v81
	v_lshlrev_b32_e32 v88, 16, v82
	v_and_b32_e32 v89, 0xffff0000, v82
	v_lshlrev_b32_e32 v82, 16, v83
	v_and_b32_e32 v83, 0xffff0000, v83
	v_pk_add_f32 v[76:77], v[76:77], v[86:87]
	v_pk_add_f32 v[78:79], v[78:79], v[80:81]
	v_pk_add_f32 v[72:73], v[72:73], v[88:89]
	v_pk_add_f32 v[74:75], v[74:75], v[82:83]
	global_store_dwordx4 v[84:85], v[76:79], off
	global_store_dwordx4 v[84:85], v[72:75], off offset:16
	s_waitcnt vmcnt(8)
	s_nop 1
	v_mov_b64_e32 v[72:73], v[212:213]
	v_mov_b64_e32 v[74:75], v[214:215]
	v_add_u32_e32 v76, 0x80, v140
	v_ashrrev_i32_e32 v77, 31, v76
	v_lshlrev_b64 v[78:79], 11, v[76:77]
	v_lshl_add_u64 v[78:79], s[10:11], 0, v[78:79]
	v_lshl_add_u64 v[78:79], v[78:79], 0, v[142:143]
	v_lshlrev_b32_e32 v80, 16, v72
	v_and_b32_e32 v81, 0xffff0000, v72
	v_lshlrev_b32_e32 v72, 16, v73
	v_and_b32_e32 v73, 0xffff0000, v73
	v_lshlrev_b32_e32 v82, 16, v74
	v_and_b32_e32 v83, 0xffff0000, v74
	v_lshlrev_b32_e32 v74, 16, v75
	v_and_b32_e32 v75, 0xffff0000, v75
	v_pk_add_f32 v[68:69], v[68:69], v[80:81]
	v_pk_add_f32 v[70:71], v[70:71], v[72:73]
	v_pk_add_f32 v[64:65], v[64:65], v[82:83]
	v_pk_add_f32 v[66:67], v[66:67], v[74:75]
	global_store_dwordx4 v[84:85], v[68:71], off offset:512
	global_store_dwordx4 v[84:85], v[64:67], off offset:528
	s_waitcnt vmcnt(7)
	s_nop 1
	v_mov_b64_e32 v[64:65], v[220:221]
	v_mov_b64_e32 v[66:67], v[222:223]
	v_lshlrev_b64 v[68:69], 12, v[76:77]
	v_lshl_add_u64 v[68:69], s[12:13], 0, v[68:69]
	v_lshl_add_u64 v[68:69], v[68:69], 0, v[138:139]
	v_lshlrev_b32_e32 v70, 16, v64
	v_and_b32_e32 v71, 0xffff0000, v64
	v_lshlrev_b32_e32 v64, 16, v65
	v_and_b32_e32 v65, 0xffff0000, v65
	v_lshlrev_b32_e32 v72, 16, v66
	v_and_b32_e32 v73, 0xffff0000, v66
	v_lshlrev_b32_e32 v66, 16, v67
	v_and_b32_e32 v67, 0xffff0000, v67
	v_pk_add_f32 v[60:61], v[60:61], v[70:71]
	v_pk_add_f32 v[62:63], v[62:63], v[64:65]
	v_pk_add_f32 v[56:57], v[56:57], v[72:73]
	v_pk_add_f32 v[58:59], v[58:59], v[66:67]
	global_store_dwordx4 v[68:69], v[60:63], off
	global_store_dwordx4 v[68:69], v[56:59], off offset:16
	s_waitcnt vmcnt(6)
	s_nop 1
	v_mov_b64_e32 v[56:57], v[224:225]
	v_mov_b64_e32 v[58:59], v[226:227]
	v_add_u32_e32 v60, 0x90, v140
	v_ashrrev_i32_e32 v61, 31, v60
	v_lshlrev_b64 v[62:63], 11, v[60:61]
	v_lshl_add_u64 v[62:63], s[10:11], 0, v[62:63]
	v_lshl_add_u64 v[62:63], v[62:63], 0, v[142:143]
	v_lshlrev_b32_e32 v64, 16, v56
	v_and_b32_e32 v65, 0xffff0000, v56
	v_lshlrev_b32_e32 v56, 16, v57
	v_and_b32_e32 v57, 0xffff0000, v57
	v_lshlrev_b32_e32 v66, 16, v58
	v_and_b32_e32 v67, 0xffff0000, v58
	v_lshlrev_b32_e32 v58, 16, v59
	v_and_b32_e32 v59, 0xffff0000, v59
	v_pk_add_f32 v[52:53], v[52:53], v[64:65]
	v_pk_add_f32 v[54:55], v[54:55], v[56:57]
	v_pk_add_f32 v[48:49], v[48:49], v[66:67]
	v_pk_add_f32 v[50:51], v[50:51], v[58:59]
	global_store_dwordx4 v[68:69], v[52:55], off offset:512
	global_store_dwordx4 v[68:69], v[48:51], off offset:528
	s_waitcnt vmcnt(5)
	s_nop 1
	v_mov_b64_e32 v[48:49], v[228:229]
	v_mov_b64_e32 v[50:51], v[230:231]
	v_lshlrev_b64 v[52:53], 12, v[60:61]
	v_lshl_add_u64 v[52:53], s[12:13], 0, v[52:53]
	v_lshl_add_u64 v[52:53], v[52:53], 0, v[138:139]
	v_lshlrev_b32_e32 v54, 16, v48
	v_and_b32_e32 v55, 0xffff0000, v48
	v_lshlrev_b32_e32 v48, 16, v49
	v_and_b32_e32 v49, 0xffff0000, v49
	v_lshlrev_b32_e32 v56, 16, v50
	v_and_b32_e32 v57, 0xffff0000, v50
	v_lshlrev_b32_e32 v50, 16, v51
	v_and_b32_e32 v51, 0xffff0000, v51
	v_pk_add_f32 v[44:45], v[44:45], v[54:55]
	v_pk_add_f32 v[46:47], v[46:47], v[48:49]
	v_pk_add_f32 v[40:41], v[40:41], v[56:57]
	v_pk_add_f32 v[42:43], v[42:43], v[50:51]
	global_store_dwordx4 v[52:53], v[44:47], off
	global_store_dwordx4 v[52:53], v[40:43], off offset:16
	s_waitcnt vmcnt(4)
	s_nop 1
	v_mov_b64_e32 v[40:41], v[232:233]
	v_mov_b64_e32 v[42:43], v[234:235]
	v_add_u32_e32 v44, 0xa0, v140
	v_ashrrev_i32_e32 v45, 31, v44
	v_lshlrev_b64 v[46:47], 11, v[44:45]
	v_lshl_add_u64 v[46:47], s[10:11], 0, v[46:47]
	v_lshl_add_u64 v[46:47], v[46:47], 0, v[142:143]
	v_lshlrev_b32_e32 v48, 16, v40
	v_and_b32_e32 v49, 0xffff0000, v40
	v_lshlrev_b32_e32 v40, 16, v41
	v_and_b32_e32 v41, 0xffff0000, v41
	v_lshlrev_b32_e32 v50, 16, v42
	v_and_b32_e32 v51, 0xffff0000, v42
	v_lshlrev_b32_e32 v42, 16, v43
	v_and_b32_e32 v43, 0xffff0000, v43
	v_pk_add_f32 v[36:37], v[36:37], v[48:49]
	v_pk_add_f32 v[38:39], v[38:39], v[40:41]
	v_pk_add_f32 v[32:33], v[32:33], v[50:51]
	v_pk_add_f32 v[34:35], v[34:35], v[42:43]
	global_store_dwordx4 v[52:53], v[36:39], off offset:512
	global_store_dwordx4 v[52:53], v[32:35], off offset:528
	s_waitcnt vmcnt(3)
	s_nop 1
	v_mov_b64_e32 v[32:33], v[184:185]
	v_mov_b64_e32 v[34:35], v[186:187]
	v_lshlrev_b64 v[36:37], 12, v[44:45]
	v_lshl_add_u64 v[36:37], s[12:13], 0, v[36:37]
	v_lshl_add_u64 v[36:37], v[36:37], 0, v[138:139]
	v_lshlrev_b32_e32 v38, 16, v32
	v_and_b32_e32 v39, 0xffff0000, v32
	v_lshlrev_b32_e32 v32, 16, v33
	v_and_b32_e32 v33, 0xffff0000, v33
	v_lshlrev_b32_e32 v40, 16, v34
	v_and_b32_e32 v41, 0xffff0000, v34
	v_lshlrev_b32_e32 v34, 16, v35
	v_and_b32_e32 v35, 0xffff0000, v35
	v_pk_add_f32 v[28:29], v[28:29], v[38:39]
	v_pk_add_f32 v[30:31], v[30:31], v[32:33]
	v_pk_add_f32 v[24:25], v[24:25], v[40:41]
	v_pk_add_f32 v[26:27], v[26:27], v[34:35]
	global_store_dwordx4 v[36:37], v[28:31], off
	global_store_dwordx4 v[36:37], v[24:27], off offset:16
	s_waitcnt vmcnt(2)
	s_nop 1
	v_mov_b64_e32 v[24:25], v[188:189]
	v_mov_b64_e32 v[26:27], v[190:191]
	v_add_u32_e32 v28, 0xb0, v140
	v_ashrrev_i32_e32 v29, 31, v28
	v_lshlrev_b64 v[30:31], 11, v[28:29]
	v_lshl_add_u64 v[30:31], s[10:11], 0, v[30:31]
	v_lshl_add_u64 v[30:31], v[30:31], 0, v[142:143]
	v_lshlrev_b32_e32 v32, 16, v24
	v_and_b32_e32 v33, 0xffff0000, v24
	v_lshlrev_b32_e32 v24, 16, v25
	v_and_b32_e32 v25, 0xffff0000, v25
	v_lshlrev_b32_e32 v34, 16, v26
	v_and_b32_e32 v35, 0xffff0000, v26
	v_lshlrev_b32_e32 v26, 16, v27
	v_and_b32_e32 v27, 0xffff0000, v27
	v_pk_add_f32 v[20:21], v[20:21], v[32:33]
	v_pk_add_f32 v[22:23], v[22:23], v[24:25]
	v_pk_add_f32 v[16:17], v[16:17], v[34:35]
	v_pk_add_f32 v[18:19], v[18:19], v[26:27]
	global_store_dwordx4 v[36:37], v[20:23], off offset:512
	global_store_dwordx4 v[36:37], v[16:19], off offset:528
	s_waitcnt vmcnt(1)
	s_nop 1
	v_mov_b64_e32 v[16:17], v[192:193]
	v_mov_b64_e32 v[18:19], v[194:195]
	v_lshlrev_b64 v[20:21], 12, v[28:29]
	v_lshl_add_u64 v[20:21], s[12:13], 0, v[20:21]
	v_lshl_add_u64 v[20:21], v[20:21], 0, v[138:139]
	v_lshlrev_b32_e32 v22, 16, v16
	v_and_b32_e32 v23, 0xffff0000, v16
	v_lshlrev_b32_e32 v16, 16, v17
	v_and_b32_e32 v17, 0xffff0000, v17
	v_lshlrev_b32_e32 v24, 16, v18
	v_and_b32_e32 v25, 0xffff0000, v18
	v_lshlrev_b32_e32 v18, 16, v19
	v_and_b32_e32 v19, 0xffff0000, v19
	v_pk_add_f32 v[12:13], v[12:13], v[22:23]
	v_pk_add_f32 v[14:15], v[14:15], v[16:17]
	v_pk_add_f32 v[8:9], v[8:9], v[24:25]
	v_pk_add_f32 v[10:11], v[10:11], v[18:19]
	global_store_dwordx4 v[20:21], v[12:15], off
	global_store_dwordx4 v[20:21], v[8:11], off offset:16
	s_waitcnt vmcnt(0)
	s_nop 1
	v_mov_b64_e32 v[8:9], v[196:197]
	v_mov_b64_e32 v[10:11], v[198:199]
	v_lshlrev_b32_e32 v12, 16, v8
	v_and_b32_e32 v13, 0xffff0000, v8
	v_lshlrev_b32_e32 v8, 16, v9
	v_and_b32_e32 v9, 0xffff0000, v9
	v_lshlrev_b32_e32 v14, 16, v10
	v_and_b32_e32 v15, 0xffff0000, v10
	v_lshlrev_b32_e32 v10, 16, v11
	v_and_b32_e32 v11, 0xffff0000, v11
	v_pk_add_f32 v[4:5], v[4:5], v[12:13]
	v_pk_add_f32 v[6:7], v[6:7], v[8:9]
	v_pk_add_f32 v[0:1], v[0:1], v[14:15]
	v_pk_add_f32 v[2:3], v[2:3], v[10:11]
	global_store_dwordx4 v[20:21], v[4:7], off offset:512
	global_store_dwordx4 v[20:21], v[0:3], off offset:528
	s_cbranch_vccnz .LBB0_919
	s_andn2_b64 vcc, exec, s[14:15]
	s_cbranch_vccnz .LBB0_918
	s_barrier
	s_branch .LBB0_918

.LBB0_954:
	v_lshl_add_u32 v140, s50, 8, v144
	v_ashrrev_i32_e32 v141, 31, v140
	v_lshl_or_b32 v138, s49, 8, v146
	v_lshlrev_b64 v[142:143], 11, v[140:141]
	v_ashrrev_i32_e32 v139, 31, v138
	v_lshl_add_u64 v[142:143], s[10:11], 0, v[142:143]
	v_lshl_add_u64 v[142:143], v[138:139], 1, v[142:143]
	v_subrev_u32_e32 v240, s10, v142
	global_load_dwordx4 v[184:187], v240, s[10:11]
	global_load_dwordx4 v[188:191], v240, s[10:11] offset:256
	v_add_u32_e32 v241, 0x8000, v240
	global_load_dwordx4 v[192:195], v241, s[10:11]
	v_add_u32_e32 v241, 0x8000, v240
	global_load_dwordx4 v[196:199], v241, s[10:11] offset:256
	v_add_u32_e32 v241, 0x10000, v240
	global_load_dwordx4 v[200:203], v241, s[10:11]
	v_add_u32_e32 v241, 0x10000, v240
	global_load_dwordx4 v[204:207], v241, s[10:11] offset:256
	v_add_u32_e32 v241, 0x18000, v240
	global_load_dwordx4 v[208:211], v241, s[10:11]
	v_add_u32_e32 v241, 0x18000, v240
	global_load_dwordx4 v[212:215], v241, s[10:11] offset:256
	v_add_u32_e32 v241, 0x40000, v240
	global_load_dwordx4 v[220:223], v241, s[10:11]
	v_add_u32_e32 v241, 0x40000, v240
	global_load_dwordx4 v[224:227], v241, s[10:11] offset:256
	v_add_u32_e32 v241, 0x48000, v240
	global_load_dwordx4 v[228:231], v241, s[10:11]
	v_add_u32_e32 v241, 0x48000, v240
	global_load_dwordx4 v[232:235], v241, s[10:11] offset:256
	s_waitcnt vmcnt(11)
	s_nop 1
	v_mov_b64_e32 v[150:151], v[184:185]
	v_mov_b64_e32 v[152:153], v[186:187]
	v_add_u32_e32 v241, 0x50000, v240
	global_load_dwordx4 v[184:187], v241, s[10:11]
	s_waitcnt vmcnt(11)
	s_nop 1
	v_mov_b64_e32 v[154:155], v[188:189]
	v_mov_b64_e32 v[156:157], v[190:191]
	v_add_u32_e32 v241, 0x50000, v240
	global_load_dwordx4 v[188:191], v241, s[10:11] offset:256
	v_and_b32_e32 v149, 64, v217
	v_xor_b32_e32 v148, 16, v217
	v_add_u32_e32 v149, 64, v149
	v_xor_b32_e32 v158, 32, v217
	v_cmp_lt_i32_e32 vcc, v148, v149
	v_and_b32_e32 v159, 0xffff0000, v150
	v_cndmask_b32_e32 v148, v217, v148, vcc
	v_cmp_lt_i32_e32 vcc, v158, v149
	v_lshlrev_b32_e32 v149, 2, v148
	v_lshlrev_b32_e32 v174, 16, v152
	v_cndmask_b32_e32 v158, v217, v158, vcc
	v_lshlrev_b32_e32 v148, 2, v158
	v_lshlrev_b32_e32 v158, 16, v150
	v_lshlrev_b32_e32 v150, 16, v151
	v_and_b32_e32 v151, 0xffff0000, v151
	v_and_b32_e32 v175, 0xffff0000, v152
	v_lshlrev_b32_e32 v152, 16, v153
	v_and_b32_e32 v153, 0xffff0000, v153
	v_lshlrev_b32_e32 v178, 16, v156
	v_and_b32_e32 v179, 0xffff0000, v156
	v_lshlrev_b32_e32 v156, 16, v157
	v_and_b32_e32 v157, 0xffff0000, v157
	v_pk_add_f32 v[124:125], v[124:125], v[158:159]
	v_lshlrev_b32_e32 v176, 16, v154
	v_and_b32_e32 v177, 0xffff0000, v154
	v_lshlrev_b32_e32 v154, 16, v155
	v_and_b32_e32 v155, 0xffff0000, v155
	v_pk_add_f32 v[126:127], v[126:127], v[150:151]
	v_pk_add_f32 v[122:123], v[122:123], v[152:153]
	v_pk_add_f32 v[152:153], v[114:115], v[156:157]
	v_pk_mul_f32 v[114:115], v[124:125], v[124:125]
	v_pk_add_f32 v[118:119], v[118:119], v[154:155]
	v_pk_mul_f32 v[154:155], v[126:127], v[126:127]
	v_add_f32_e32 v114, v114, v115
	v_pk_add_f32 v[120:121], v[120:121], v[174:175]
	v_add_f32_e32 v114, v154, v114
	v_pk_mul_f32 v[156:157], v[120:121], v[120:121]
	v_add_f32_e32 v114, v155, v114
	v_add_f32_e32 v114, v156, v114
	v_pk_mul_f32 v[158:159], v[122:123], v[122:123]
	v_add_f32_e32 v114, v157, v114
	v_pk_add_f32 v[116:117], v[116:117], v[176:177]
	v_add_f32_e32 v114, v158, v114
	v_pk_add_f32 v[150:151], v[112:113], v[178:179]
	v_cvt_pk_bf16_f32 v112, v124, v125
	v_pk_mul_f32 v[124:125], v[116:117], v[116:117]
	v_add_f32_e32 v114, v159, v114
	v_add_f32_e32 v114, v124, v114
	v_cvt_pk_bf16_f32 v113, v126, v127
	v_pk_mul_f32 v[126:127], v[118:119], v[118:119]
	v_add_f32_e32 v114, v125, v114
	v_add_f32_e32 v114, v126, v114
	v_pk_mul_f32 v[174:175], v[150:151], v[150:151]
	v_add_f32_e32 v114, v127, v114
	v_add_f32_e32 v114, v174, v114
	v_pk_mul_f32 v[176:177], v[152:153], v[152:153]
	v_add_f32_e32 v114, v175, v114
	v_add_f32_e32 v114, v176, v114
	v_add_f32_e32 v124, v177, v114
	ds_bpermute_b32 v125, v149, v124
	v_cvt_pk_bf16_f32 v114, v120, v121
	v_cvt_pk_bf16_f32 v115, v122, v123
	global_store_dwordx4 v[142:143], v[112:115], off
	s_waitcnt lgkmcnt(0)
	s_nop 0
	v_add_f32_e32 v112, v124, v125
	ds_bpermute_b32 v113, v148, v112
	v_cvt_pk_bf16_f32 v114, v116, v117
	v_cvt_pk_bf16_f32 v115, v118, v119
	v_cvt_pk_bf16_f32 v116, v150, v151
	v_cvt_pk_bf16_f32 v117, v152, v153
	global_store_dwordx4 v[142:143], v[114:117], off offset:256
	s_and_saveexec_b64 s[22:23], s[4:5]
	s_cbranch_execz .LBB0_956
	s_waitcnt lgkmcnt(0)
	v_add_f32_e32 v114, v112, v113
	v_lshl_add_u64 v[112:113], v[140:141], 2, s[14:15]
	global_atomic_add_f32 v[112:113], v114, off
.LBB0_956:
	s_or_b64 exec, exec, s[22:23]
	v_or_b32_e32 v112, 16, v140
	s_waitcnt lgkmcnt(0)
	v_ashrrev_i32_e32 v113, 31, v112
	v_lshlrev_b64 v[114:115], 11, v[112:113]
	v_lshl_add_u64 v[114:115], s[10:11], 0, v[114:115]
	v_lshl_add_u64 v[114:115], v[138:139], 1, v[114:115]
	s_waitcnt vmcnt(11)
	s_nop 1
	v_mov_b64_e32 v[116:117], v[192:193]
	v_mov_b64_e32 v[118:119], v[194:195]
	v_add_u32_e32 v241, 0x58000, v240
	global_load_dwordx4 v[192:195], v241, s[10:11]
	s_waitcnt vmcnt(11)
	s_nop 1
	v_mov_b64_e32 v[120:121], v[196:197]
	v_mov_b64_e32 v[122:123], v[198:199]
	v_add_u32_e32 v241, 0x58000, v240
	global_load_dwordx4 v[196:199], v241, s[10:11] offset:256
	v_lshlrev_b32_e32 v124, 16, v116
	v_and_b32_e32 v125, 0xffff0000, v116
	v_lshlrev_b32_e32 v116, 16, v117
	v_and_b32_e32 v117, 0xffff0000, v117
	v_lshlrev_b32_e32 v126, 16, v118
	v_and_b32_e32 v127, 0xffff0000, v118
	v_lshlrev_b32_e32 v118, 16, v119
	v_and_b32_e32 v119, 0xffff0000, v119
	v_lshlrev_b32_e32 v150, 16, v122
	v_and_b32_e32 v151, 0xffff0000, v122
	v_lshlrev_b32_e32 v122, 16, v123
	v_and_b32_e32 v123, 0xffff0000, v123
	v_pk_add_f32 v[108:109], v[108:109], v[124:125]
	v_lshlrev_b32_e32 v142, 16, v120
	v_and_b32_e32 v143, 0xffff0000, v120
	v_lshlrev_b32_e32 v120, 16, v121
	v_and_b32_e32 v121, 0xffff0000, v121
	v_pk_add_f32 v[110:111], v[110:111], v[116:117]
	v_pk_add_f32 v[106:107], v[106:107], v[118:119]
	v_pk_add_f32 v[118:119], v[98:99], v[122:123]
	v_pk_mul_f32 v[98:99], v[108:109], v[108:109]
	v_pk_add_f32 v[102:103], v[102:103], v[120:121]
	v_pk_mul_f32 v[120:121], v[110:111], v[110:111]
	v_add_f32_e32 v98, v98, v99
	v_pk_add_f32 v[104:105], v[104:105], v[126:127]
	v_add_f32_e32 v98, v120, v98
	v_pk_mul_f32 v[122:123], v[104:105], v[104:105]
	v_add_f32_e32 v98, v121, v98
	v_add_f32_e32 v98, v122, v98
	v_pk_mul_f32 v[124:125], v[106:107], v[106:107]
	v_add_f32_e32 v98, v123, v98
	v_pk_add_f32 v[100:101], v[100:101], v[142:143]
	v_add_f32_e32 v98, v124, v98
	v_pk_add_f32 v[116:117], v[96:97], v[150:151]
	v_cvt_pk_bf16_f32 v96, v108, v109
	v_pk_mul_f32 v[108:109], v[100:101], v[100:101]
	v_add_f32_e32 v98, v125, v98
	v_add_f32_e32 v98, v108, v98
	v_cvt_pk_bf16_f32 v97, v110, v111
	v_pk_mul_f32 v[110:111], v[102:103], v[102:103]
	v_add_f32_e32 v98, v109, v98
	v_add_f32_e32 v98, v110, v98
	v_pk_mul_f32 v[126:127], v[116:117], v[116:117]
	v_add_f32_e32 v98, v111, v98
	v_add_f32_e32 v98, v126, v98
	v_pk_mul_f32 v[142:143], v[118:119], v[118:119]
	v_add_f32_e32 v98, v127, v98
	v_add_f32_e32 v98, v142, v98
	v_add_f32_e32 v108, v143, v98
	ds_bpermute_b32 v109, v149, v108
	v_cvt_pk_bf16_f32 v98, v104, v105
	v_cvt_pk_bf16_f32 v99, v106, v107
	global_store_dwordx4 v[114:115], v[96:99], off
	s_waitcnt lgkmcnt(0)
	s_nop 0
	v_add_f32_e32 v96, v108, v109
	ds_bpermute_b32 v97, v148, v96
	v_cvt_pk_bf16_f32 v98, v100, v101
	v_cvt_pk_bf16_f32 v99, v102, v103
	v_cvt_pk_bf16_f32 v100, v116, v117
	v_cvt_pk_bf16_f32 v101, v118, v119
	global_store_dwordx4 v[114:115], v[98:101], off offset:256
	s_and_saveexec_b64 s[22:23], s[4:5]
	s_cbranch_execz .LBB0_958
	s_waitcnt lgkmcnt(0)
	v_add_f32_e32 v98, v96, v97
	v_lshl_add_u64 v[96:97], v[112:113], 2, s[14:15]
	global_atomic_add_f32 v[96:97], v98, off
.LBB0_958:
	s_or_b64 exec, exec, s[22:23]
	v_or_b32_e32 v96, 32, v140
	s_waitcnt lgkmcnt(0)
	v_ashrrev_i32_e32 v97, 31, v96
	v_lshlrev_b64 v[98:99], 11, v[96:97]
	v_lshl_add_u64 v[98:99], s[10:11], 0, v[98:99]
	v_lshl_add_u64 v[98:99], v[138:139], 1, v[98:99]
	s_waitcnt vmcnt(11)
	s_nop 1
	v_mov_b64_e32 v[100:101], v[200:201]
	v_mov_b64_e32 v[102:103], v[202:203]
	s_waitcnt vmcnt(10)
	s_nop 1
	v_mov_b64_e32 v[104:105], v[204:205]
	v_mov_b64_e32 v[106:107], v[206:207]
	v_lshlrev_b32_e32 v108, 16, v100
	v_and_b32_e32 v109, 0xffff0000, v100
	v_lshlrev_b32_e32 v100, 16, v101
	v_and_b32_e32 v101, 0xffff0000, v101
	v_lshlrev_b32_e32 v110, 16, v102
	v_and_b32_e32 v111, 0xffff0000, v102
	v_lshlrev_b32_e32 v102, 16, v103
	v_and_b32_e32 v103, 0xffff0000, v103
	v_lshlrev_b32_e32 v114, 16, v106
	v_and_b32_e32 v115, 0xffff0000, v106
	v_lshlrev_b32_e32 v106, 16, v107
	v_and_b32_e32 v107, 0xffff0000, v107
	v_pk_add_f32 v[92:93], v[92:93], v[108:109]
	v_lshlrev_b32_e32 v112, 16, v104
	v_and_b32_e32 v113, 0xffff0000, v104
	v_lshlrev_b32_e32 v104, 16, v105
	v_and_b32_e32 v105, 0xffff0000, v105
	v_pk_add_f32 v[94:95], v[94:95], v[100:101]
	v_pk_add_f32 v[90:91], v[90:91], v[102:103]
	v_pk_add_f32 v[102:103], v[82:83], v[106:107]
	v_pk_mul_f32 v[82:83], v[92:93], v[92:93]
	v_pk_add_f32 v[86:87], v[86:87], v[104:105]
	v_pk_mul_f32 v[104:105], v[94:95], v[94:95]
	v_add_f32_e32 v82, v82, v83
	v_pk_add_f32 v[88:89], v[88:89], v[110:111]
	v_add_f32_e32 v82, v104, v82
	v_pk_mul_f32 v[106:107], v[88:89], v[88:89]
	v_add_f32_e32 v82, v105, v82
	v_add_f32_e32 v82, v106, v82
	v_pk_mul_f32 v[108:109], v[90:91], v[90:91]
	v_add_f32_e32 v82, v107, v82
	v_pk_add_f32 v[84:85], v[84:85], v[112:113]
	v_add_f32_e32 v82, v108, v82
	v_pk_add_f32 v[100:101], v[80:81], v[114:115]
	v_cvt_pk_bf16_f32 v80, v92, v93
	v_pk_mul_f32 v[92:93], v[84:85], v[84:85]
	v_add_f32_e32 v82, v109, v82
	v_add_f32_e32 v82, v92, v82
	v_cvt_pk_bf16_f32 v81, v94, v95
	v_pk_mul_f32 v[94:95], v[86:87], v[86:87]
	v_add_f32_e32 v82, v93, v82
	v_add_f32_e32 v82, v94, v82
	v_pk_mul_f32 v[110:111], v[100:101], v[100:101]
	v_add_f32_e32 v82, v95, v82
	v_add_f32_e32 v82, v110, v82
	v_pk_mul_f32 v[112:113], v[102:103], v[102:103]
	v_add_f32_e32 v82, v111, v82
	v_add_f32_e32 v82, v112, v82
	v_add_f32_e32 v92, v113, v82
	ds_bpermute_b32 v93, v149, v92
	v_cvt_pk_bf16_f32 v82, v88, v89
	v_cvt_pk_bf16_f32 v83, v90, v91
	global_store_dwordx4 v[98:99], v[80:83], off
	s_waitcnt lgkmcnt(0)
	s_nop 0
	v_add_f32_e32 v80, v92, v93
	ds_bpermute_b32 v81, v148, v80
	v_cvt_pk_bf16_f32 v82, v84, v85
	v_cvt_pk_bf16_f32 v83, v86, v87
	v_cvt_pk_bf16_f32 v84, v100, v101
	v_cvt_pk_bf16_f32 v85, v102, v103
	global_store_dwordx4 v[98:99], v[82:85], off offset:256
	s_and_saveexec_b64 s[22:23], s[4:5]
	s_cbranch_execz .LBB0_960
	s_waitcnt lgkmcnt(0)
	v_add_f32_e32 v82, v80, v81
	v_lshl_add_u64 v[80:81], v[96:97], 2, s[14:15]
	global_atomic_add_f32 v[80:81], v82, off
.LBB0_960:
	s_or_b64 exec, exec, s[22:23]
	v_or_b32_e32 v80, 48, v140
	s_waitcnt lgkmcnt(0)
	v_ashrrev_i32_e32 v81, 31, v80
	v_lshlrev_b64 v[82:83], 11, v[80:81]
	v_lshl_add_u64 v[82:83], s[10:11], 0, v[82:83]
	v_lshl_add_u64 v[82:83], v[138:139], 1, v[82:83]
	s_waitcnt vmcnt(9)
	s_nop 1
	v_mov_b64_e32 v[84:85], v[208:209]
	v_mov_b64_e32 v[86:87], v[210:211]
	s_waitcnt vmcnt(8)
	s_nop 1
	v_mov_b64_e32 v[88:89], v[212:213]
	v_mov_b64_e32 v[90:91], v[214:215]
	v_lshlrev_b32_e32 v92, 16, v84
	v_and_b32_e32 v93, 0xffff0000, v84
	v_lshlrev_b32_e32 v84, 16, v85
	v_and_b32_e32 v85, 0xffff0000, v85
	v_lshlrev_b32_e32 v94, 16, v86
	v_and_b32_e32 v95, 0xffff0000, v86
	v_lshlrev_b32_e32 v86, 16, v87
	v_and_b32_e32 v87, 0xffff0000, v87
	v_lshlrev_b32_e32 v98, 16, v90
	v_and_b32_e32 v99, 0xffff0000, v90
	v_lshlrev_b32_e32 v90, 16, v91
	v_and_b32_e32 v91, 0xffff0000, v91
	v_pk_add_f32 v[76:77], v[76:77], v[92:93]
	v_lshlrev_b32_e32 v96, 16, v88
	v_and_b32_e32 v97, 0xffff0000, v88
	v_lshlrev_b32_e32 v88, 16, v89
	v_and_b32_e32 v89, 0xffff0000, v89
	v_pk_add_f32 v[78:79], v[78:79], v[84:85]
	v_pk_add_f32 v[74:75], v[74:75], v[86:87]
	v_pk_add_f32 v[86:87], v[66:67], v[90:91]
	v_pk_mul_f32 v[66:67], v[76:77], v[76:77]
	v_pk_add_f32 v[70:71], v[70:71], v[88:89]
	v_pk_mul_f32 v[88:89], v[78:79], v[78:79]
	v_add_f32_e32 v66, v66, v67
	v_pk_add_f32 v[72:73], v[72:73], v[94:95]
	v_add_f32_e32 v66, v88, v66
	v_pk_mul_f32 v[90:91], v[72:73], v[72:73]
	v_add_f32_e32 v66, v89, v66
	v_add_f32_e32 v66, v90, v66
	v_pk_mul_f32 v[92:93], v[74:75], v[74:75]
	v_add_f32_e32 v66, v91, v66
	v_pk_add_f32 v[68:69], v[68:69], v[96:97]
	v_add_f32_e32 v66, v92, v66
	v_pk_add_f32 v[84:85], v[64:65], v[98:99]
	v_cvt_pk_bf16_f32 v64, v76, v77
	v_pk_mul_f32 v[76:77], v[68:69], v[68:69]
	v_add_f32_e32 v66, v93, v66
	v_add_f32_e32 v66, v76, v66
	v_cvt_pk_bf16_f32 v65, v78, v79
	v_pk_mul_f32 v[78:79], v[70:71], v[70:71]
	v_add_f32_e32 v66, v77, v66
	v_add_f32_e32 v66, v78, v66
	v_pk_mul_f32 v[94:95], v[84:85], v[84:85]
	v_add_f32_e32 v66, v79, v66
	v_add_f32_e32 v66, v94, v66
	v_pk_mul_f32 v[96:97], v[86:87], v[86:87]
	v_add_f32_e32 v66, v95, v66
	v_add_f32_e32 v66, v96, v66
	v_add_f32_e32 v76, v97, v66
	ds_bpermute_b32 v77, v149, v76
	v_cvt_pk_bf16_f32 v66, v72, v73
	v_cvt_pk_bf16_f32 v67, v74, v75
	global_store_dwordx4 v[82:83], v[64:67], off
	s_waitcnt lgkmcnt(0)
	s_nop 0
	v_add_f32_e32 v64, v76, v77
	ds_bpermute_b32 v65, v148, v64
	v_cvt_pk_bf16_f32 v66, v68, v69
	v_cvt_pk_bf16_f32 v67, v70, v71
	v_cvt_pk_bf16_f32 v68, v84, v85
	v_cvt_pk_bf16_f32 v69, v86, v87
	global_store_dwordx4 v[82:83], v[66:69], off offset:256
	s_and_saveexec_b64 s[22:23], s[4:5]
	s_cbranch_execz .LBB0_962
	s_waitcnt lgkmcnt(0)
	v_add_f32_e32 v66, v64, v65
	v_lshl_add_u64 v[64:65], v[80:81], 2, s[14:15]
	global_atomic_add_f32 v[64:65], v66, off
.LBB0_962:
	s_or_b64 exec, exec, s[22:23]
	v_add_u32_e32 v64, 0x80, v140
	s_waitcnt lgkmcnt(0)
	v_ashrrev_i32_e32 v65, 31, v64
	v_lshlrev_b64 v[66:67], 11, v[64:65]
	v_lshl_add_u64 v[66:67], s[10:11], 0, v[66:67]
	v_lshl_add_u64 v[66:67], v[138:139], 1, v[66:67]
	s_waitcnt vmcnt(7)
	s_nop 1
	v_mov_b64_e32 v[68:69], v[220:221]
	v_mov_b64_e32 v[70:71], v[222:223]
	s_waitcnt vmcnt(6)
	s_nop 1
	v_mov_b64_e32 v[72:73], v[224:225]
	v_mov_b64_e32 v[74:75], v[226:227]
	v_lshlrev_b32_e32 v76, 16, v68
	v_and_b32_e32 v77, 0xffff0000, v68
	v_lshlrev_b32_e32 v68, 16, v69
	v_and_b32_e32 v69, 0xffff0000, v69
	v_lshlrev_b32_e32 v78, 16, v70
	v_and_b32_e32 v79, 0xffff0000, v70
	v_lshlrev_b32_e32 v70, 16, v71
	v_and_b32_e32 v71, 0xffff0000, v71
	v_lshlrev_b32_e32 v82, 16, v74
	v_and_b32_e32 v83, 0xffff0000, v74
	v_lshlrev_b32_e32 v74, 16, v75
	v_and_b32_e32 v75, 0xffff0000, v75
	v_pk_add_f32 v[60:61], v[60:61], v[76:77]
	v_lshlrev_b32_e32 v80, 16, v72
	v_and_b32_e32 v81, 0xffff0000, v72
	v_lshlrev_b32_e32 v72, 16, v73
	v_and_b32_e32 v73, 0xffff0000, v73
	v_pk_add_f32 v[62:63], v[62:63], v[68:69]
	v_pk_add_f32 v[58:59], v[58:59], v[70:71]
	v_pk_add_f32 v[70:71], v[50:51], v[74:75]
	v_pk_mul_f32 v[50:51], v[60:61], v[60:61]
	v_pk_add_f32 v[54:55], v[54:55], v[72:73]
	v_pk_mul_f32 v[72:73], v[62:63], v[62:63]
	v_add_f32_e32 v50, v50, v51
	v_pk_add_f32 v[56:57], v[56:57], v[78:79]
	v_add_f32_e32 v50, v72, v50
	v_pk_mul_f32 v[74:75], v[56:57], v[56:57]
	v_add_f32_e32 v50, v73, v50
	v_add_f32_e32 v50, v74, v50
	v_pk_mul_f32 v[76:77], v[58:59], v[58:59]
	v_add_f32_e32 v50, v75, v50
	v_pk_add_f32 v[52:53], v[52:53], v[80:81]
	v_add_f32_e32 v50, v76, v50
	v_pk_add_f32 v[68:69], v[48:49], v[82:83]
	v_cvt_pk_bf16_f32 v48, v60, v61
	v_pk_mul_f32 v[60:61], v[52:53], v[52:53]
	v_add_f32_e32 v50, v77, v50
	v_add_f32_e32 v50, v60, v50
	v_cvt_pk_bf16_f32 v49, v62, v63
	v_pk_mul_f32 v[62:63], v[54:55], v[54:55]
	v_add_f32_e32 v50, v61, v50
	v_add_f32_e32 v50, v62, v50
	v_pk_mul_f32 v[78:79], v[68:69], v[68:69]
	v_add_f32_e32 v50, v63, v50
	v_add_f32_e32 v50, v78, v50
	v_pk_mul_f32 v[80:81], v[70:71], v[70:71]
	v_add_f32_e32 v50, v79, v50
	v_add_f32_e32 v50, v80, v50
	v_add_f32_e32 v60, v81, v50
	ds_bpermute_b32 v61, v149, v60
	v_cvt_pk_bf16_f32 v50, v56, v57
	v_cvt_pk_bf16_f32 v51, v58, v59
	global_store_dwordx4 v[66:67], v[48:51], off
	s_waitcnt lgkmcnt(0)
	s_nop 0
	v_add_f32_e32 v48, v60, v61
	ds_bpermute_b32 v49, v148, v48
	v_cvt_pk_bf16_f32 v50, v52, v53
	v_cvt_pk_bf16_f32 v51, v54, v55
	v_cvt_pk_bf16_f32 v52, v68, v69
	v_cvt_pk_bf16_f32 v53, v70, v71
	global_store_dwordx4 v[66:67], v[50:53], off offset:256
	s_and_saveexec_b64 s[22:23], s[4:5]
	s_cbranch_execz .LBB0_964
	s_waitcnt lgkmcnt(0)
	v_add_f32_e32 v50, v48, v49
	v_lshl_add_u64 v[48:49], v[64:65], 2, s[14:15]
	global_atomic_add_f32 v[48:49], v50, off
.LBB0_964:
	s_or_b64 exec, exec, s[22:23]
	v_add_u32_e32 v48, 0x90, v140
	s_waitcnt lgkmcnt(0)
	v_ashrrev_i32_e32 v49, 31, v48
	v_lshlrev_b64 v[50:51], 11, v[48:49]
	v_lshl_add_u64 v[50:51], s[10:11], 0, v[50:51]
	v_lshl_add_u64 v[50:51], v[138:139], 1, v[50:51]
	s_waitcnt vmcnt(5)
	s_nop 1
	v_mov_b64_e32 v[52:53], v[228:229]
	v_mov_b64_e32 v[54:55], v[230:231]
	s_waitcnt vmcnt(4)
	s_nop 1
	v_mov_b64_e32 v[56:57], v[232:233]
	v_mov_b64_e32 v[58:59], v[234:235]
	v_lshlrev_b32_e32 v60, 16, v52
	v_and_b32_e32 v61, 0xffff0000, v52
	v_lshlrev_b32_e32 v52, 16, v53
	v_and_b32_e32 v53, 0xffff0000, v53
	v_lshlrev_b32_e32 v62, 16, v54
	v_and_b32_e32 v63, 0xffff0000, v54
	v_lshlrev_b32_e32 v54, 16, v55
	v_and_b32_e32 v55, 0xffff0000, v55
	v_lshlrev_b32_e32 v66, 16, v58
	v_and_b32_e32 v67, 0xffff0000, v58
	v_lshlrev_b32_e32 v58, 16, v59
	v_and_b32_e32 v59, 0xffff0000, v59
	v_pk_add_f32 v[44:45], v[44:45], v[60:61]
	v_lshlrev_b32_e32 v64, 16, v56
	v_and_b32_e32 v65, 0xffff0000, v56
	v_lshlrev_b32_e32 v56, 16, v57
	v_and_b32_e32 v57, 0xffff0000, v57
	v_pk_add_f32 v[46:47], v[46:47], v[52:53]
	v_pk_add_f32 v[42:43], v[42:43], v[54:55]
	v_pk_add_f32 v[54:55], v[34:35], v[58:59]
	v_pk_mul_f32 v[34:35], v[44:45], v[44:45]
	v_pk_add_f32 v[38:39], v[38:39], v[56:57]
	v_pk_mul_f32 v[56:57], v[46:47], v[46:47]
	v_add_f32_e32 v34, v34, v35
	v_pk_add_f32 v[40:41], v[40:41], v[62:63]
	v_add_f32_e32 v34, v56, v34
	v_pk_mul_f32 v[58:59], v[40:41], v[40:41]
	v_add_f32_e32 v34, v57, v34
	v_add_f32_e32 v34, v58, v34
	v_pk_mul_f32 v[60:61], v[42:43], v[42:43]
	v_add_f32_e32 v34, v59, v34
	v_pk_add_f32 v[36:37], v[36:37], v[64:65]
	v_add_f32_e32 v34, v60, v34
	v_pk_add_f32 v[52:53], v[32:33], v[66:67]
	v_cvt_pk_bf16_f32 v32, v44, v45
	v_pk_mul_f32 v[44:45], v[36:37], v[36:37]
	v_add_f32_e32 v34, v61, v34
	v_add_f32_e32 v34, v44, v34
	v_cvt_pk_bf16_f32 v33, v46, v47
	v_pk_mul_f32 v[46:47], v[38:39], v[38:39]
	v_add_f32_e32 v34, v45, v34
	v_add_f32_e32 v34, v46, v34
	v_pk_mul_f32 v[62:63], v[52:53], v[52:53]
	v_add_f32_e32 v34, v47, v34
	v_add_f32_e32 v34, v62, v34
	v_pk_mul_f32 v[64:65], v[54:55], v[54:55]
	v_add_f32_e32 v34, v63, v34
	v_add_f32_e32 v34, v64, v34
	v_add_f32_e32 v44, v65, v34
	ds_bpermute_b32 v45, v149, v44
	v_cvt_pk_bf16_f32 v34, v40, v41
	v_cvt_pk_bf16_f32 v35, v42, v43
	global_store_dwordx4 v[50:51], v[32:35], off
	s_waitcnt lgkmcnt(0)
	s_nop 0
	v_add_f32_e32 v32, v44, v45
	ds_bpermute_b32 v33, v148, v32
	v_cvt_pk_bf16_f32 v34, v36, v37
	v_cvt_pk_bf16_f32 v35, v38, v39
	v_cvt_pk_bf16_f32 v36, v52, v53
	v_cvt_pk_bf16_f32 v37, v54, v55
	global_store_dwordx4 v[50:51], v[34:37], off offset:256
	s_and_saveexec_b64 s[22:23], s[4:5]
	s_cbranch_execz .LBB0_966
	s_waitcnt lgkmcnt(0)
	v_add_f32_e32 v34, v32, v33
	v_lshl_add_u64 v[32:33], v[48:49], 2, s[14:15]
	global_atomic_add_f32 v[32:33], v34, off
.LBB0_966:
	s_or_b64 exec, exec, s[22:23]
	v_add_u32_e32 v32, 0xa0, v140
	s_waitcnt lgkmcnt(0)
	v_ashrrev_i32_e32 v33, 31, v32
	v_lshlrev_b64 v[34:35], 11, v[32:33]
	v_lshl_add_u64 v[34:35], s[10:11], 0, v[34:35]
	v_lshl_add_u64 v[34:35], v[138:139], 1, v[34:35]
	s_waitcnt vmcnt(3)
	s_nop 1
	v_mov_b64_e32 v[36:37], v[184:185]
	v_mov_b64_e32 v[38:39], v[186:187]
	s_waitcnt vmcnt(2)
	s_nop 1
	v_mov_b64_e32 v[40:41], v[188:189]
	v_mov_b64_e32 v[42:43], v[190:191]
	v_lshlrev_b32_e32 v44, 16, v36
	v_and_b32_e32 v45, 0xffff0000, v36
	v_lshlrev_b32_e32 v36, 16, v37
	v_and_b32_e32 v37, 0xffff0000, v37
	v_lshlrev_b32_e32 v46, 16, v38
	v_and_b32_e32 v47, 0xffff0000, v38
	v_lshlrev_b32_e32 v38, 16, v39
	v_and_b32_e32 v39, 0xffff0000, v39
	v_lshlrev_b32_e32 v50, 16, v42
	v_and_b32_e32 v51, 0xffff0000, v42
	v_lshlrev_b32_e32 v42, 16, v43
	v_and_b32_e32 v43, 0xffff0000, v43
	v_pk_add_f32 v[28:29], v[28:29], v[44:45]
	v_lshlrev_b32_e32 v48, 16, v40
	v_and_b32_e32 v49, 0xffff0000, v40
	v_lshlrev_b32_e32 v40, 16, v41
	v_and_b32_e32 v41, 0xffff0000, v41
	v_pk_add_f32 v[30:31], v[30:31], v[36:37]
	v_pk_add_f32 v[26:27], v[26:27], v[38:39]
	v_pk_add_f32 v[38:39], v[18:19], v[42:43]
	v_pk_mul_f32 v[18:19], v[28:29], v[28:29]
	v_pk_add_f32 v[22:23], v[22:23], v[40:41]
	v_pk_mul_f32 v[40:41], v[30:31], v[30:31]
	v_add_f32_e32 v18, v18, v19
	v_pk_add_f32 v[24:25], v[24:25], v[46:47]
	v_add_f32_e32 v18, v40, v18
	v_pk_mul_f32 v[42:43], v[24:25], v[24:25]
	v_add_f32_e32 v18, v41, v18
	v_add_f32_e32 v18, v42, v18
	v_pk_mul_f32 v[44:45], v[26:27], v[26:27]
	v_add_f32_e32 v18, v43, v18
	v_pk_add_f32 v[20:21], v[20:21], v[48:49]
	v_add_f32_e32 v18, v44, v18
	v_pk_add_f32 v[36:37], v[16:17], v[50:51]
	v_cvt_pk_bf16_f32 v16, v28, v29
	v_pk_mul_f32 v[28:29], v[20:21], v[20:21]
	v_add_f32_e32 v18, v45, v18
	v_add_f32_e32 v18, v28, v18
	v_cvt_pk_bf16_f32 v17, v30, v31
	v_pk_mul_f32 v[30:31], v[22:23], v[22:23]
	v_add_f32_e32 v18, v29, v18
	v_add_f32_e32 v18, v30, v18
	v_pk_mul_f32 v[46:47], v[36:37], v[36:37]
	v_add_f32_e32 v18, v31, v18
	v_add_f32_e32 v18, v46, v18
	v_pk_mul_f32 v[48:49], v[38:39], v[38:39]
	v_add_f32_e32 v18, v47, v18
	v_add_f32_e32 v18, v48, v18
	v_add_f32_e32 v28, v49, v18
	ds_bpermute_b32 v29, v149, v28
	v_cvt_pk_bf16_f32 v18, v24, v25
	v_cvt_pk_bf16_f32 v19, v26, v27
	global_store_dwordx4 v[34:35], v[16:19], off
	s_waitcnt lgkmcnt(0)
	s_nop 0
	v_add_f32_e32 v16, v28, v29
	ds_bpermute_b32 v17, v148, v16
	v_cvt_pk_bf16_f32 v18, v20, v21
	v_cvt_pk_bf16_f32 v19, v22, v23
	v_cvt_pk_bf16_f32 v20, v36, v37
	v_cvt_pk_bf16_f32 v21, v38, v39
	global_store_dwordx4 v[34:35], v[18:21], off offset:256
	s_and_saveexec_b64 s[22:23], s[4:5]
	s_cbranch_execz .LBB0_968
	s_waitcnt lgkmcnt(0)
	v_add_f32_e32 v18, v16, v17
	v_lshl_add_u64 v[16:17], v[32:33], 2, s[14:15]
	global_atomic_add_f32 v[16:17], v18, off
.LBB0_968:
	s_or_b64 exec, exec, s[22:23]
	v_add_u32_e32 v16, 0xb0, v140
	s_waitcnt lgkmcnt(0)
	v_ashrrev_i32_e32 v17, 31, v16
	v_lshlrev_b64 v[18:19], 11, v[16:17]
	v_lshl_add_u64 v[18:19], s[10:11], 0, v[18:19]
	v_lshl_add_u64 v[18:19], v[138:139], 1, v[18:19]
	s_waitcnt vmcnt(1)
	s_nop 1
	v_mov_b64_e32 v[20:21], v[192:193]
	v_mov_b64_e32 v[22:23], v[194:195]
	s_waitcnt vmcnt(0)
	s_nop 1
	v_mov_b64_e32 v[24:25], v[196:197]
	v_mov_b64_e32 v[26:27], v[198:199]
	v_lshlrev_b32_e32 v28, 16, v20
	v_and_b32_e32 v29, 0xffff0000, v20
	v_lshlrev_b32_e32 v20, 16, v21
	v_and_b32_e32 v21, 0xffff0000, v21
	v_lshlrev_b32_e32 v30, 16, v22
	v_and_b32_e32 v31, 0xffff0000, v22
	v_lshlrev_b32_e32 v22, 16, v23
	v_and_b32_e32 v23, 0xffff0000, v23
	v_lshlrev_b32_e32 v34, 16, v26
	v_and_b32_e32 v35, 0xffff0000, v26
	v_lshlrev_b32_e32 v26, 16, v27
	v_and_b32_e32 v27, 0xffff0000, v27
	v_pk_add_f32 v[12:13], v[12:13], v[28:29]
	v_lshlrev_b32_e32 v32, 16, v24
	v_and_b32_e32 v33, 0xffff0000, v24
	v_lshlrev_b32_e32 v24, 16, v25
	v_and_b32_e32 v25, 0xffff0000, v25
	v_pk_add_f32 v[14:15], v[14:15], v[20:21]
	v_pk_add_f32 v[10:11], v[10:11], v[22:23]
	v_pk_add_f32 v[22:23], v[2:3], v[26:27]
	v_pk_mul_f32 v[2:3], v[12:13], v[12:13]
	v_pk_add_f32 v[6:7], v[6:7], v[24:25]
	v_pk_mul_f32 v[24:25], v[14:15], v[14:15]
	v_add_f32_e32 v2, v2, v3
	v_pk_add_f32 v[8:9], v[8:9], v[30:31]
	v_add_f32_e32 v2, v24, v2
	v_pk_mul_f32 v[26:27], v[8:9], v[8:9]
	v_add_f32_e32 v2, v25, v2
	v_add_f32_e32 v2, v26, v2
	v_pk_mul_f32 v[28:29], v[10:11], v[10:11]
	v_add_f32_e32 v2, v27, v2
	v_pk_add_f32 v[4:5], v[4:5], v[32:33]
	v_add_f32_e32 v2, v28, v2
	v_pk_add_f32 v[20:21], v[0:1], v[34:35]
	v_cvt_pk_bf16_f32 v0, v12, v13
	v_pk_mul_f32 v[12:13], v[4:5], v[4:5]
	v_add_f32_e32 v2, v29, v2
	v_add_f32_e32 v2, v12, v2
	v_cvt_pk_bf16_f32 v1, v14, v15
	v_pk_mul_f32 v[14:15], v[6:7], v[6:7]
	v_add_f32_e32 v2, v13, v2
	v_add_f32_e32 v2, v14, v2
	v_pk_mul_f32 v[30:31], v[20:21], v[20:21]
	v_add_f32_e32 v2, v15, v2
	v_add_f32_e32 v2, v30, v2
	v_pk_mul_f32 v[32:33], v[22:23], v[22:23]
	v_add_f32_e32 v2, v31, v2
	v_add_f32_e32 v2, v32, v2
	v_add_f32_e32 v12, v33, v2
	ds_bpermute_b32 v13, v149, v12
	v_cvt_pk_bf16_f32 v2, v8, v9
	v_cvt_pk_bf16_f32 v3, v10, v11
	global_store_dwordx4 v[18:19], v[0:3], off
	s_waitcnt lgkmcnt(0)
	s_nop 0
	v_add_f32_e32 v0, v12, v13
	ds_bpermute_b32 v1, v148, v0
	v_cvt_pk_bf16_f32 v2, v4, v5
	v_cvt_pk_bf16_f32 v3, v6, v7
	v_cvt_pk_bf16_f32 v4, v20, v21
	v_cvt_pk_bf16_f32 v5, v22, v23
	global_store_dwordx4 v[18:19], v[2:5], off offset:256
	s_and_saveexec_b64 s[22:23], s[4:5]
	s_cbranch_execz .LBB0_970
	s_waitcnt lgkmcnt(0)
	v_add_f32_e32 v2, v0, v1
	v_lshl_add_u64 v[0:1], v[16:17], 2, s[14:15]
	global_atomic_add_f32 v[0:1], v2, off
